# v74 + mixer units de-serialised: gMLP staging loads of all four row groups issued up front (one wait), attention K/V staging loads all in flight before the LDS writes
# baseline (speedup 1.0000x reference)
.LBB0_421:
	s_cmpk_gt_i32 s29, 0xff
	s_mov_b64 s[4:5], -1
	s_cbranch_scc0 .LBB0_423
	s_lshl_b32 s4, s29, 4
	v_mov_b32_e32 v3, v183
	s_and_b32 s8, s4, 0x7fffff80
	s_addk_i32 s8, 0xf000
	v_ashrrev_i32_e32 v28, 4, v3
	v_add_u32_e32 v0, s8, v28
	v_ashrrev_i32_e32 v1, 31, v0
	v_lshlrev_b64 v[4:5], 6, v[0:1]
	v_lshl_add_u64 v[4:5], s[0:1], 0, v[4:5]
	global_load_dwordx4 v[6:9], v[4:5], off offset:32
	global_load_dwordx4 v[10:13], v[4:5], off offset:16
	global_load_dwordx4 v[14:17], v[4:5], off offset:48
	global_load_dwordx4 v[22:25], v[4:5], off
	v_mov_b32_e32 v178, 0x800
	v_mov_b32_e32 v179, 0
	v_lshl_add_u64 v[176:177], v[4:5], 0, v[178:179]
	global_load_dwordx4 v[128:131], v[176:177], off
	global_load_dwordx4 v[132:135], v[176:177], off offset:16
	global_load_dwordx4 v[136:139], v[176:177], off offset:32
	global_load_dwordx4 v[140:143], v[176:177], off offset:48
	v_lshl_add_u64 v[176:177], v[176:177], 0, v[178:179]
	global_load_dwordx4 v[144:147], v[176:177], off
	global_load_dwordx4 v[148:151], v[176:177], off offset:16
	global_load_dwordx4 v[152:155], v[176:177], off offset:32
	global_load_dwordx4 v[156:159], v[176:177], off offset:48
	v_lshl_add_u64 v[176:177], v[176:177], 0, v[178:179]
	global_load_dwordx4 v[160:163], v[176:177], off
	global_load_dwordx4 v[164:167], v[176:177], off offset:16
	global_load_dwordx4 v[168:171], v[176:177], off offset:32
	global_load_dwordx4 v[172:175], v[176:177], off offset:48
	s_and_b32 s6, s29, 7
	v_lshlrev_b64 v[0:1], 11, v[0:1]
	s_lshl_b32 s76, s6, 8
	v_and_b32_e32 v4, 15, v3
	v_lshl_add_u64 v[0:1], s[72:73], 0, v[0:1]
	v_lshlrev_b32_e32 v20, 4, v4
	v_lshl_add_u64 v[0:1], v[0:1], 0, s[76:77]
	v_readlane_b32 s36, v254, 30
	v_lshl_add_u64 v[0:1], v[0:1], 0, v[20:21]
	s_lshl_b32 s9, s6, 7
	s_lshl_b32 s4, s6, 9
	v_readlane_b32 s44, v254, 38
	global_load_dwordx4 v[34:37], v[0:1], off
	v_mov_b32_e32 v178, 0x10000
	v_lshl_add_u64 v[176:177], v[0:1], 0, v[178:179]
	global_load_dwordx4 v[188:191], v[176:177], off
	v_lshl_add_u64 v[176:177], v[176:177], 0, v[178:179]
	global_load_dwordx4 v[192:195], v[176:177], off
	v_lshl_add_u64 v[176:177], v[176:177], 0, v[178:179]
	global_load_dwordx4 v[196:199], v[176:177], off
	v_readlane_b32 s45, v254, 39
	s_add_u32 s4, s44, s4
	v_lshlrev_b32_e32 v0, 5, v4
	s_addc_u32 s5, s45, 0
	global_load_dwordx4 v[38:41], v0, s[4:5]
	global_load_dwordx4 v[42:45], v0, s[4:5] offset:16
	v_readlane_b32 s46, v254, 40
	s_lshl_b32 s6, s6, 16
	v_readlane_b32 s47, v254, 41
	v_lshlrev_b32_e32 v18, 7, v28
	s_add_u32 s6, s46, s6
	v_ashrrev_i32_e32 v19, 31, v18
	s_addc_u32 s7, s47, 0
	v_mov_b32_e32 v1, v21
	v_lshl_add_u64 v[18:19], v[18:19], 2, s[6:7]
	v_lshl_add_u64 v[18:19], v[18:19], 0, v[0:1]
	global_load_dwordx4 v[208:211], v[18:19], off
	global_load_dwordx4 v[212:215], v[18:19], off offset:16
	v_mov_b32_e32 v178, 0x4000
	v_lshl_add_u64 v[176:177], v[18:19], 0, v[178:179]
	global_load_dwordx4 v[216:219], v[176:177], off
	global_load_dwordx4 v[220:223], v[176:177], off offset:16
	v_lshl_add_u64 v[176:177], v[176:177], 0, v[178:179]
	global_load_dwordx4 v[224:227], v[176:177], off
	global_load_dwordx4 v[228:231], v[176:177], off offset:16
	v_lshl_add_u64 v[176:177], v[176:177], 0, v[178:179]
	global_load_dwordx4 v[232:235], v[176:177], off
	global_load_dwordx4 v[236:239], v[176:177], off offset:16
	s_movk_i32 s10, 0x880
	v_readlane_b32 s48, v254, 42
	v_readlane_b32 s49, v254, 43
	v_readlane_b32 s37, v254, 31
	v_readlane_b32 s38, v254, 32
	v_readlane_b32 s39, v254, 33
	v_readlane_b32 s40, v254, 34
	v_readlane_b32 s41, v254, 35
	v_readlane_b32 s42, v254, 36
	v_readlane_b32 s43, v254, 37
	v_readlane_b32 s50, v254, 44
	v_readlane_b32 s51, v254, 45
	s_waitcnt vmcnt(0)
	v_mov_b32_e32 v200, v38
	v_mov_b32_e32 v201, v39
	v_mov_b32_e32 v202, v40
	v_mov_b32_e32 v203, v41
	v_mov_b32_e32 v204, v42
	v_mov_b32_e32 v205, v43
	v_mov_b32_e32 v206, v44
	v_mov_b32_e32 v207, v45
	v_mov_b32_e32 v27, v6
	v_mov_b32_e32 v47, v8
	v_mov_b32_e32 v48, v10
	v_mov_b32_e32 v49, v14
	v_mov_b32_e32 v14, v11
	v_mov_b32_e32 v10, v12
	v_mov_b32_e32 v11, v16
	v_mov_b32_e32 v16, v13
	v_mov_b32_e32 v26, v22
	v_mov_b32_e32 v6, v23
	v_mov_b32_e32 v46, v24
	v_mov_b32_e32 v8, v25
	v_pk_add_f32 v[12:13], v[48:49], v[14:15]
	v_pk_add_f32 v[10:11], v[10:11], v[16:17]
	v_pk_add_f32 v[6:7], v[26:27], v[6:7]
	v_pk_add_f32 v[8:9], v[46:47], v[8:9]
	v_pk_add_f32 v[10:11], v[12:13], v[10:11]
	v_pk_add_f32 v[6:7], v[6:7], v[8:9]
	v_lshlrev_b32_e32 v12, 16, v34
	v_pk_add_f32 v[6:7], v[6:7], v[10:11]
	v_and_b32_e32 v13, 0xffff0000, v34
	v_add_f32_e32 v2, v6, v7
	v_fmamk_f32 v2, v2, 0x3a800000, v29
	v_mul_f32_e32 v5, 0x4b800000, v2
	v_cmp_gt_f32_e32 vcc, s21, v2
	v_lshlrev_b32_e32 v16, 16, v36
	v_and_b32_e32 v17, 0xffff0000, v36
	v_cndmask_b32_e32 v2, v2, v5, vcc
	v_rsq_f32_e32 v2, v2
	v_lshlrev_b32_e32 v14, 16, v35
	v_and_b32_e32 v15, 0xffff0000, v35
	v_lshlrev_b32_e32 v6, 16, v37
	v_mul_f32_e32 v5, 0x45800000, v2
	v_cndmask_b32_e32 v2, v2, v5, vcc
	v_and_b32_e32 v7, 0xffff0000, v37
	v_pk_mul_f32 v[8:9], v[2:3], v[12:13] op_sel_hi:[0,1]
	v_pk_mul_f32 v[12:13], v[2:3], v[16:17] op_sel_hi:[0,1]
	v_pk_mul_f32 v[10:11], v[2:3], v[14:15] op_sel_hi:[0,1]
	v_pk_mul_f32 v[6:7], v[2:3], v[6:7] op_sel_hi:[0,1]
	v_pk_mul_f32 v[12:13], v[42:43], v[12:13]
	v_pk_mul_f32 v[10:11], v[40:41], v[10:11]
	v_pk_mul_f32 v[8:9], v[38:39], v[8:9]
	v_pk_mul_f32 v[6:7], v[44:45], v[6:7]
	s_nop 1
	v_cvt_pk_bf16_f32 v36, v8, v9
	s_nop 1
	v_cvt_pk_bf16_f32 v37, v10, v11
	s_nop 1
	v_cvt_pk_bf16_f32 v13, v12, v13
	v_mad_u32_u24 v12, v4, s10, 16
	s_nop 1
	v_cvt_pk_bf16_f32 v38, v6, v7
	v_mov_b32_e32 v14, v208
	v_mov_b32_e32 v15, v209
	v_mov_b32_e32 v16, v210
	v_mov_b32_e32 v17, v211
	v_mov_b32_e32 v22, v212
	v_mov_b32_e32 v23, v213
	v_mov_b32_e32 v24, v214
	v_mov_b32_e32 v25, v215
	v_lshlrev_b32_e32 v7, 3, v4
	v_mov_b32_e32 v2, s77
	v_lshl_add_u32 v19, v28, 1, v12
	v_or_b32_e32 v11, 4, v7
	v_cmp_gt_i32_e32 vcc, v7, v28
	v_mov_b32_e32 v18, s77
	ds_write_b16 v19, v36
	ds_write_b16_d16_hi v19, v36 offset:272
	ds_write_b16 v19, v37 offset:544
	ds_write_b16_d16_hi v19, v37 offset:816
	ds_write_b16 v19, v13 offset:1088
	ds_write_b16_d16_hi v19, v13 offset:1360
	ds_write_b16 v19, v38 offset:1632
	ds_write_b16_d16_hi v19, v38 offset:1904
	v_or_b32_e32 v8, 5, v7
	v_add_u32_e32 v5, 0x200, v3
	v_or_b32_e32 v9, 6, v7
	v_ashrrev_i32_e32 v58, 4, v5
	v_or_b32_e32 v10, 7, v7
	v_or_b32_e32 v5, 2, v7
	v_add_u32_e32 v26, s8, v58
	v_or_b32_e32 v6, 3, v7
	v_ashrrev_i32_e32 v27, 31, v26
	v_lshlrev_b64 v[34:35], 6, v[26:27]
	v_lshl_add_u64 v[42:43], s[0:1], 0, v[34:35]
	s_movk_i32 s10, 0xf790
	s_waitcnt vmcnt(1)
	v_cndmask_b32_e32 v13, v16, v16, vcc
	v_cndmask_b32_e32 v19, v17, v17, vcc
	v_cndmask_b32_e32 v2, v14, v2, vcc
	v_cmp_gt_i32_e32 vcc, v11, v28
	s_waitcnt vmcnt(0)
	s_nop 0
	v_cndmask_b32_e32 v18, v22, v18, vcc
	v_cndmask_b32_e32 v22, v25, v25, vcc
	v_cndmask_b32_e32 v24, v24, v24, vcc
	v_cndmask_b32_e32 v23, v23, v23, vcc
	v_cmp_lt_i32_e32 vcc, v7, v28
	s_nop 1
	v_cndmask_b32_e32 v2, v2, v14, vcc
	v_cndmask_b32_e32 v14, v19, v17, vcc
	v_cndmask_b32_e32 v13, v13, v16, vcc
	v_cndmask_b32_e32 v15, 0, v15, vcc
	v_cmp_le_i32_e32 vcc, v8, v28
	s_nop 1
	v_cndmask_b32_e32 v16, 0, v23, vcc
	v_cmp_le_i32_e32 vcc, v9, v28
	s_nop 1
	v_cndmask_b32_e32 v17, 0, v24, vcc
	v_cmp_le_i32_e32 vcc, v10, v28
	s_nop 1
	v_cndmask_b32_e32 v19, 0, v22, vcc
	v_cmp_le_i32_e32 vcc, v5, v28
	s_nop 1
	v_cndmask_b32_e32 v13, 0, v13, vcc
	v_cmp_le_i32_e32 vcc, v6, v28
	s_nop 1
	v_cndmask_b32_e32 v22, 0, v14, vcc
	s_nop 1
	v_cvt_pk_bf16_f32 v14, v2, v15
	s_nop 1
	v_cvt_pk_bf16_f32 v15, v13, v22
	s_nop 1
	v_cvt_pk_bf16_f32 v16, v18, v16
	s_nop 1
	v_cvt_pk_bf16_f32 v17, v17, v19
	v_mov_b32_e32 v22, v128
	v_mov_b32_e32 v23, v129
	v_mov_b32_e32 v24, v130
	v_mov_b32_e32 v25, v131
	v_mov_b32_e32 v34, v136
	v_mov_b32_e32 v35, v137
	v_mov_b32_e32 v36, v138
	v_mov_b32_e32 v37, v139
	v_mov_b32_e32 v38, v132
	v_mov_b32_e32 v39, v133
	v_mov_b32_e32 v40, v134
	v_mov_b32_e32 v41, v135
	s_nop 0
	v_mov_b32_e32 v42, v140
	v_mov_b32_e32 v43, v141
	v_mov_b32_e32 v44, v142
	v_mov_b32_e32 v45, v143
	v_lshlrev_b64 v[18:19], 11, v[26:27]
	v_lshl_add_u64 v[18:19], s[72:73], 0, v[18:19]
	v_lshl_add_u64 v[18:19], v[18:19], 0, s[76:77]
	v_lshl_add_u64 v[18:19], v[18:19], 0, v[20:21]
	v_mov_b32_e32 v46, v188
	v_mov_b32_e32 v47, v189
	v_mov_b32_e32 v48, v190
	v_mov_b32_e32 v49, v191
	v_mov_b32_e32 v50, v200
	v_mov_b32_e32 v51, v201
	v_mov_b32_e32 v52, v202
	v_mov_b32_e32 v53, v203
	v_mov_b32_e32 v54, v204
	v_mov_b32_e32 v55, v205
	v_mov_b32_e32 v56, v206
	v_mov_b32_e32 v57, v207
	v_mad_i32_i24 v2, v4, s10, v12
	v_mad_u64_u32 v[26:27], s[10:11], v28, s24, v[2:3]
	ds_write_b128 v26, v[14:17] offset:34816
	v_lshlrev_b32_e32 v18, 7, v58
	v_ashrrev_i32_e32 v19, 31, v18
	v_lshl_add_u64 v[18:19], v[18:19], 2, s[6:7]
	v_lshl_add_u64 v[18:19], v[18:19], 0, v[0:1]
	s_waitcnt vmcnt(6)
	v_mov_b32_e32 v14, v22
	s_waitcnt vmcnt(5)
	v_mov_b32_e32 v15, v34
	v_mov_b32_e32 v34, v23
	v_mov_b32_e32 v16, v24
	v_mov_b32_e32 v17, v36
	v_mov_b32_e32 v36, v25
	s_waitcnt vmcnt(4)
	v_mov_b32_e32 v22, v38
	s_waitcnt vmcnt(3)
	v_mov_b32_e32 v23, v42
	v_mov_b32_e32 v42, v39
	v_mov_b32_e32 v24, v40
	v_mov_b32_e32 v25, v44
	v_mov_b32_e32 v44, v41
	v_pk_add_f32 v[14:15], v[14:15], v[34:35]
	v_pk_add_f32 v[16:17], v[16:17], v[36:37]
	v_pk_add_f32 v[22:23], v[22:23], v[42:43]
	v_pk_add_f32 v[24:25], v[24:25], v[44:45]
	v_pk_add_f32 v[14:15], v[14:15], v[16:17]
	v_pk_add_f32 v[16:17], v[22:23], v[24:25]
	s_waitcnt vmcnt(2)
	v_lshlrev_b32_e32 v26, 16, v46
	v_pk_add_f32 v[14:15], v[14:15], v[16:17]
	v_and_b32_e32 v27, 0xffff0000, v46
	v_add_f32_e32 v13, v14, v15
	v_fmamk_f32 v13, v13, 0x3a800000, v29
	v_mul_f32_e32 v14, 0x4b800000, v13
	v_cmp_gt_f32_e32 vcc, s21, v13
	v_lshlrev_b32_e32 v38, 16, v47
	v_and_b32_e32 v39, 0xffff0000, v47
	v_cndmask_b32_e32 v13, v13, v14, vcc
	v_rsq_f32_e32 v13, v13
	v_lshlrev_b32_e32 v40, 16, v48
	v_and_b32_e32 v41, 0xffff0000, v48
	v_lshlrev_b32_e32 v14, 16, v49
	v_mul_f32_e32 v16, 0x45800000, v13
	v_and_b32_e32 v15, 0xffff0000, v49
	v_cndmask_b32_e32 v16, v13, v16, vcc
	v_pk_mul_f32 v[22:23], v[16:17], v[26:27] op_sel_hi:[0,1]
	v_pk_mul_f32 v[24:25], v[16:17], v[38:39] op_sel_hi:[0,1]
	v_pk_mul_f32 v[26:27], v[16:17], v[40:41] op_sel_hi:[0,1]
	v_pk_mul_f32 v[14:15], v[16:17], v[14:15] op_sel_hi:[0,1]
	s_waitcnt vmcnt(1)
	v_pk_mul_f32 v[16:17], v[52:53], v[24:25]
	v_pk_mul_f32 v[22:23], v[50:51], v[22:23]
	s_waitcnt vmcnt(0)
	v_pk_mul_f32 v[14:15], v[56:57], v[14:15]
	v_pk_mul_f32 v[24:25], v[54:55], v[26:27]
	s_nop 1
	v_cvt_pk_bf16_f32 v13, v22, v23
	s_nop 1
	v_cvt_pk_bf16_f32 v27, v16, v17
	v_cmp_gt_i32_e32 vcc, v7, v58
	s_nop 1
	v_cvt_pk_bf16_f32 v28, v24, v25
	s_nop 1
	v_cvt_pk_bf16_f32 v36, v14, v15
	v_mov_b32_e32 v14, v216
	v_mov_b32_e32 v15, v217
	v_mov_b32_e32 v16, v218
	v_mov_b32_e32 v17, v219
	v_mov_b32_e32 v22, v220
	v_mov_b32_e32 v23, v221
	v_mov_b32_e32 v24, v222
	v_mov_b32_e32 v25, v223
	v_add_u32_e32 v19, 0x400, v3
	v_mov_b32_e32 v18, s77
	v_ashrrev_i32_e32 v59, 4, v19
	v_lshl_add_u32 v19, v58, 1, v12
	v_mov_b32_e32 v26, s77
	ds_write_b16 v19, v13
	ds_write_b16_d16_hi v19, v13 offset:272
	ds_write_b16 v19, v27 offset:544
	ds_write_b16_d16_hi v19, v27 offset:816
	ds_write_b16 v19, v28 offset:1088
	ds_write_b16_d16_hi v19, v28 offset:1360
	ds_write_b16 v19, v36 offset:1632
	ds_write_b16_d16_hi v19, v36 offset:1904
	v_add_u32_e32 v46, s8, v59
	v_ashrrev_i32_e32 v47, 31, v46
	v_lshlrev_b64 v[34:35], 6, v[46:47]
	v_lshl_add_u64 v[42:43], s[0:1], 0, v[34:35]
	s_waitcnt vmcnt(1)
	v_cndmask_b32_e32 v13, v16, v16, vcc
	v_cndmask_b32_e32 v19, v17, v17, vcc
	v_cndmask_b32_e32 v18, v14, v18, vcc
	v_cmp_gt_i32_e32 vcc, v11, v58
	s_waitcnt vmcnt(0)
	s_nop 0
	v_cndmask_b32_e32 v22, v22, v26, vcc
	v_cndmask_b32_e32 v25, v25, v25, vcc
	v_cndmask_b32_e32 v24, v24, v24, vcc
	v_cndmask_b32_e32 v23, v23, v23, vcc
	v_cmp_lt_i32_e32 vcc, v7, v58
	v_mad_u64_u32 v[26:27], s[10:11], v58, s24, v[2:3]
	s_nop 0
	v_cndmask_b32_e32 v14, v18, v14, vcc
	v_cndmask_b32_e32 v17, v19, v17, vcc
	v_cndmask_b32_e32 v13, v13, v16, vcc
	v_cndmask_b32_e32 v15, 0, v15, vcc
	v_cmp_le_i32_e32 vcc, v8, v58
	s_nop 1
	v_cvt_pk_bf16_f32 v14, v14, v15
	s_nop 1
	v_cndmask_b32_e32 v16, 0, v23, vcc
	v_cmp_le_i32_e32 vcc, v9, v58
	s_nop 1
	v_cndmask_b32_e32 v18, 0, v24, vcc
	v_cmp_le_i32_e32 vcc, v10, v58
	s_nop 1
	v_cndmask_b32_e32 v19, 0, v25, vcc
	v_cmp_le_i32_e32 vcc, v5, v58
	s_nop 1
	v_cndmask_b32_e32 v13, 0, v13, vcc
	v_cmp_le_i32_e32 vcc, v6, v58
	s_nop 1
	v_cndmask_b32_e32 v17, 0, v17, vcc
	s_nop 1
	v_cvt_pk_bf16_f32 v15, v13, v17
	s_nop 1
	v_cvt_pk_bf16_f32 v16, v22, v16
	s_nop 1
	v_cvt_pk_bf16_f32 v17, v18, v19
	v_mov_b32_e32 v22, v144
	v_mov_b32_e32 v23, v145
	v_mov_b32_e32 v24, v146
	v_mov_b32_e32 v25, v147
	v_mov_b32_e32 v34, v152
	v_mov_b32_e32 v35, v153
	v_mov_b32_e32 v36, v154
	v_mov_b32_e32 v37, v155
	v_mov_b32_e32 v38, v148
	v_mov_b32_e32 v39, v149
	v_mov_b32_e32 v40, v150
	v_mov_b32_e32 v41, v151
	s_nop 0
	v_mov_b32_e32 v42, v156
	v_mov_b32_e32 v43, v157
	v_mov_b32_e32 v44, v158
	v_mov_b32_e32 v45, v159
	v_lshlrev_b64 v[18:19], 11, v[46:47]
	v_lshl_add_u64 v[18:19], s[72:73], 0, v[18:19]
	v_lshl_add_u64 v[18:19], v[18:19], 0, s[76:77]
	v_lshl_add_u64 v[18:19], v[18:19], 0, v[20:21]
	v_mov_b32_e32 v46, v192
	v_mov_b32_e32 v47, v193
	v_mov_b32_e32 v48, v194
	v_mov_b32_e32 v49, v195
	v_mov_b32_e32 v50, v200
	v_mov_b32_e32 v51, v201
	v_mov_b32_e32 v52, v202
	v_mov_b32_e32 v53, v203
	v_mov_b32_e32 v54, v204
	v_mov_b32_e32 v55, v205
	v_mov_b32_e32 v56, v206
	v_mov_b32_e32 v57, v207
	ds_write_b128 v26, v[14:17] offset:34816
	v_lshlrev_b32_e32 v18, 7, v59
	v_ashrrev_i32_e32 v19, 31, v18
	v_lshl_add_u64 v[18:19], v[18:19], 2, s[6:7]
	v_lshl_add_u64 v[18:19], v[18:19], 0, v[0:1]
	s_waitcnt vmcnt(6)
	v_mov_b32_e32 v14, v22
	s_waitcnt vmcnt(5)
	v_mov_b32_e32 v15, v34
	v_mov_b32_e32 v34, v23
	v_mov_b32_e32 v16, v24
	v_mov_b32_e32 v17, v36
	v_mov_b32_e32 v36, v25
	s_waitcnt vmcnt(4)
	v_mov_b32_e32 v22, v38
	s_waitcnt vmcnt(3)
	v_mov_b32_e32 v23, v42
	v_mov_b32_e32 v42, v39
	v_mov_b32_e32 v24, v40
	v_mov_b32_e32 v25, v44
	v_mov_b32_e32 v44, v41
	v_pk_add_f32 v[14:15], v[14:15], v[34:35]
	v_pk_add_f32 v[16:17], v[16:17], v[36:37]
	v_pk_add_f32 v[22:23], v[22:23], v[42:43]
	v_pk_add_f32 v[24:25], v[24:25], v[44:45]
	v_pk_add_f32 v[14:15], v[14:15], v[16:17]
	v_pk_add_f32 v[16:17], v[22:23], v[24:25]
	s_waitcnt vmcnt(2)
	v_lshlrev_b32_e32 v26, 16, v46
	v_pk_add_f32 v[14:15], v[14:15], v[16:17]
	v_and_b32_e32 v27, 0xffff0000, v46
	v_add_f32_e32 v13, v14, v15
	v_fmamk_f32 v13, v13, 0x3a800000, v29
	v_mul_f32_e32 v14, 0x4b800000, v13
	v_cmp_gt_f32_e32 vcc, s21, v13
	v_lshlrev_b32_e32 v38, 16, v47
	v_and_b32_e32 v39, 0xffff0000, v47
	v_cndmask_b32_e32 v13, v13, v14, vcc
	v_rsq_f32_e32 v13, v13
	v_lshlrev_b32_e32 v40, 16, v48
	v_and_b32_e32 v41, 0xffff0000, v48
	v_lshlrev_b32_e32 v14, 16, v49
	v_mul_f32_e32 v16, 0x45800000, v13
	v_and_b32_e32 v15, 0xffff0000, v49
	v_cndmask_b32_e32 v16, v13, v16, vcc
	v_pk_mul_f32 v[22:23], v[16:17], v[26:27] op_sel_hi:[0,1]
	v_pk_mul_f32 v[24:25], v[16:17], v[38:39] op_sel_hi:[0,1]
	v_pk_mul_f32 v[26:27], v[16:17], v[40:41] op_sel_hi:[0,1]
	v_pk_mul_f32 v[14:15], v[16:17], v[14:15] op_sel_hi:[0,1]
	s_waitcnt vmcnt(1)
	v_pk_mul_f32 v[16:17], v[52:53], v[24:25]
	v_pk_mul_f32 v[22:23], v[50:51], v[22:23]
	s_waitcnt vmcnt(0)
	v_pk_mul_f32 v[14:15], v[56:57], v[14:15]
	v_pk_mul_f32 v[24:25], v[54:55], v[26:27]
	s_nop 1
	v_cvt_pk_bf16_f32 v13, v22, v23
	s_nop 1
	v_cvt_pk_bf16_f32 v27, v16, v17
	v_cmp_gt_i32_e32 vcc, v7, v59
	s_nop 1
	v_cvt_pk_bf16_f32 v28, v24, v25
	s_nop 1
	v_cvt_pk_bf16_f32 v36, v14, v15
	v_mov_b32_e32 v14, v224
	v_mov_b32_e32 v15, v225
	v_mov_b32_e32 v16, v226
	v_mov_b32_e32 v17, v227
	v_mov_b32_e32 v22, v228
	v_mov_b32_e32 v23, v229
	v_mov_b32_e32 v24, v230
	v_mov_b32_e32 v25, v231
	v_add_u32_e32 v19, 0x600, v3
	v_mov_b32_e32 v18, s77
	v_ashrrev_i32_e32 v58, 4, v19
	v_lshl_add_u32 v19, v59, 1, v12
	v_mov_b32_e32 v26, s77
	ds_write_b16 v19, v13
	ds_write_b16_d16_hi v19, v13 offset:272
	ds_write_b16 v19, v27 offset:544
	ds_write_b16_d16_hi v19, v27 offset:816
	ds_write_b16 v19, v28 offset:1088
	ds_write_b16_d16_hi v19, v28 offset:1360
	ds_write_b16 v19, v36 offset:1632
	ds_write_b16_d16_hi v19, v36 offset:1904
	v_add_u32_e32 v46, s8, v58
	v_ashrrev_i32_e32 v47, 31, v46
	v_lshlrev_b64 v[34:35], 6, v[46:47]
	v_lshl_add_u64 v[42:43], s[0:1], 0, v[34:35]
	s_waitcnt vmcnt(1)
	v_cndmask_b32_e32 v13, v16, v16, vcc
	v_cndmask_b32_e32 v19, v17, v17, vcc
	v_cndmask_b32_e32 v18, v14, v18, vcc
	v_cmp_gt_i32_e32 vcc, v11, v59
	s_waitcnt vmcnt(0)
	s_nop 0
	v_cndmask_b32_e32 v22, v22, v26, vcc
	v_cndmask_b32_e32 v25, v25, v25, vcc
	v_cndmask_b32_e32 v24, v24, v24, vcc
	v_cndmask_b32_e32 v23, v23, v23, vcc
	v_cmp_lt_i32_e32 vcc, v7, v59
	s_nop 1
	v_cndmask_b32_e32 v14, v18, v14, vcc
	v_cndmask_b32_e32 v17, v19, v17, vcc
	v_cndmask_b32_e32 v13, v13, v16, vcc
	v_cndmask_b32_e32 v15, 0, v15, vcc
	v_cmp_le_i32_e32 vcc, v8, v59
	s_nop 1
	v_cvt_pk_bf16_f32 v14, v14, v15
	s_nop 1
	v_cndmask_b32_e32 v16, 0, v23, vcc
	v_cmp_le_i32_e32 vcc, v9, v59
	s_nop 1
	v_cndmask_b32_e32 v18, 0, v24, vcc
	v_cmp_le_i32_e32 vcc, v10, v59
	s_nop 1
	v_cndmask_b32_e32 v19, 0, v25, vcc
	v_cmp_le_i32_e32 vcc, v5, v59
	s_nop 1
	v_cndmask_b32_e32 v13, 0, v13, vcc
	v_cmp_le_i32_e32 vcc, v6, v59
	s_nop 1
	v_cndmask_b32_e32 v17, 0, v17, vcc
	s_nop 1
	v_cvt_pk_bf16_f32 v15, v13, v17
	s_nop 1
	v_cvt_pk_bf16_f32 v16, v22, v16
	s_nop 1
	v_cvt_pk_bf16_f32 v17, v18, v19
	v_mov_b32_e32 v22, v160
	v_mov_b32_e32 v23, v161
	v_mov_b32_e32 v24, v162
	v_mov_b32_e32 v25, v163
	v_mov_b32_e32 v34, v168
	v_mov_b32_e32 v35, v169
	v_mov_b32_e32 v36, v170
	v_mov_b32_e32 v37, v171
	v_mov_b32_e32 v38, v164
	v_mov_b32_e32 v39, v165
	v_mov_b32_e32 v40, v166
	v_mov_b32_e32 v41, v167
	s_nop 0
	v_mov_b32_e32 v42, v172
	v_mov_b32_e32 v43, v173
	v_mov_b32_e32 v44, v174
	v_mov_b32_e32 v45, v175
	v_lshlrev_b64 v[18:19], 11, v[46:47]
	v_lshl_add_u64 v[18:19], s[72:73], 0, v[18:19]
	v_lshl_add_u64 v[18:19], v[18:19], 0, s[76:77]
	v_lshl_add_u64 v[18:19], v[18:19], 0, v[20:21]
	v_mov_b32_e32 v46, v196
	v_mov_b32_e32 v47, v197
	v_mov_b32_e32 v48, v198
	v_mov_b32_e32 v49, v199
	v_mov_b32_e32 v50, v200
	v_mov_b32_e32 v51, v201
	v_mov_b32_e32 v52, v202
	v_mov_b32_e32 v53, v203
	v_mov_b32_e32 v54, v204
	v_mov_b32_e32 v55, v205
	v_mov_b32_e32 v56, v206
	v_mov_b32_e32 v57, v207
	v_lshlrev_b32_e32 v18, 7, v58
	v_ashrrev_i32_e32 v19, 31, v18
	v_mad_u64_u32 v[26:27], s[4:5], v59, s24, v[2:3]
	v_lshl_add_u64 v[18:19], v[18:19], 2, s[6:7]
	v_lshl_add_u64 v[0:1], v[18:19], 0, v[0:1]
	ds_write_b128 v26, v[14:17] offset:34816
	s_waitcnt vmcnt(6)
	v_mov_b32_e32 v14, v22
	s_waitcnt vmcnt(5)
	v_mov_b32_e32 v15, v34
	v_mov_b32_e32 v34, v23
	v_mov_b32_e32 v16, v24
	v_mov_b32_e32 v17, v36
	v_mov_b32_e32 v36, v25
	s_waitcnt vmcnt(4)
	v_mov_b32_e32 v18, v38
	s_waitcnt vmcnt(3)
	v_mov_b32_e32 v19, v42
	v_mov_b32_e32 v42, v39
	v_mov_b32_e32 v22, v40
	v_mov_b32_e32 v23, v44
	v_mov_b32_e32 v44, v41
	v_pk_add_f32 v[14:15], v[14:15], v[34:35]
	v_pk_add_f32 v[16:17], v[16:17], v[36:37]
	v_pk_add_f32 v[18:19], v[18:19], v[42:43]
	v_pk_add_f32 v[22:23], v[22:23], v[44:45]
	v_pk_add_f32 v[14:15], v[14:15], v[16:17]
	v_pk_add_f32 v[16:17], v[18:19], v[22:23]
	s_waitcnt vmcnt(2)
	v_lshlrev_b32_e32 v24, 16, v46
	v_pk_add_f32 v[14:15], v[14:15], v[16:17]
	v_and_b32_e32 v25, 0xffff0000, v46
	v_add_f32_e32 v13, v14, v15
	v_fmamk_f32 v13, v13, 0x3a800000, v29
	v_mul_f32_e32 v14, 0x4b800000, v13
	v_cmp_gt_f32_e32 vcc, s21, v13
	v_lshlrev_b32_e32 v26, 16, v47
	v_and_b32_e32 v27, 0xffff0000, v47
	v_cndmask_b32_e32 v13, v13, v14, vcc
	v_rsq_f32_e32 v13, v13
	v_lshlrev_b32_e32 v38, 16, v48
	v_and_b32_e32 v39, 0xffff0000, v48
	v_lshlrev_b32_e32 v14, 16, v49
	v_mul_f32_e32 v16, 0x45800000, v13
	v_and_b32_e32 v15, 0xffff0000, v49
	v_cndmask_b32_e32 v16, v13, v16, vcc
	v_pk_mul_f32 v[18:19], v[16:17], v[24:25] op_sel_hi:[0,1]
	v_pk_mul_f32 v[22:23], v[16:17], v[26:27] op_sel_hi:[0,1]
	v_pk_mul_f32 v[24:25], v[16:17], v[38:39] op_sel_hi:[0,1]
	v_pk_mul_f32 v[14:15], v[16:17], v[14:15] op_sel_hi:[0,1]
	s_waitcnt vmcnt(1)
	v_pk_mul_f32 v[16:17], v[52:53], v[22:23]
	s_waitcnt vmcnt(0)
	v_pk_mul_f32 v[14:15], v[56:57], v[14:15]
	v_pk_mul_f32 v[22:23], v[54:55], v[24:25]
	v_pk_mul_f32 v[18:19], v[50:51], v[18:19]
	v_ashrrev_i32_e32 v41, 2, v3
	s_nop 1
	v_cvt_pk_bf16_f32 v28, v18, v19
	s_nop 1
	v_cvt_pk_bf16_f32 v38, v16, v17
	s_nop 1
	v_cvt_pk_bf16_f32 v39, v22, v23
	s_nop 1
	v_cvt_pk_bf16_f32 v15, v14, v15
	v_mov_b32_e32 v22, v232
	v_mov_b32_e32 v23, v233
	v_mov_b32_e32 v24, v234
	v_mov_b32_e32 v25, v235
	v_mov_b32_e32 v34, v236
	v_mov_b32_e32 v35, v237
	v_mov_b32_e32 v36, v238
	v_mov_b32_e32 v37, v239
	v_mov_b32_e32 v0, s77
	v_bfe_u32 v40, v3, 4, 2
	v_and_b32_e32 v1, -16, v41
	v_or_b32_e32 v13, s9, v4
	v_cmp_gt_i32_e32 vcc, v7, v58
	v_mov_b32_e32 v14, s77
	v_lshl_add_u32 v42, v58, 1, v12
	v_ashrrev_i32_e32 v17, 31, v1
	v_lshl_or_b32 v16, v40, 2, v1
	v_lshlrev_b32_e32 v46, 2, v13
	v_mad_u64_u32 v[12:13], s[4:5], v58, s24, v[2:3]
	ds_write_b16 v42, v28
	ds_write_b16_d16_hi v42, v28 offset:272
	ds_write_b16 v42, v38 offset:544
	ds_write_b16_d16_hi v42, v38 offset:816
	ds_write_b16 v42, v39 offset:1088
	ds_write_b16_d16_hi v42, v39 offset:1360
	ds_write_b16 v42, v15 offset:1632
	ds_write_b16_d16_hi v42, v15 offset:1904
	v_or_b32_e32 v18, s8, v4
	v_lshl_or_b32 v20, v18, 10, s9
	v_lshl_add_u64 v[18:19], v[16:17], 0, v[20:21]
	v_lshlrev_b64 v[18:19], 1, v[18:19]
	v_lshl_add_u64 v[26:27], s[54:55], 0, v[18:19]
	v_lshl_add_u64 v[18:19], s[74:75], 0, v[18:19]
	v_mov_b32_e32 v43, v21
	v_or_b32_e32 v42, 0x14000, v20
	s_waitcnt vmcnt(1)
	v_cndmask_b32_e32 v1, v24, v24, vcc
	v_cndmask_b32_e32 v2, v25, v25, vcc
	v_cndmask_b32_e32 v0, v22, v0, vcc
	v_cmp_gt_i32_e32 vcc, v11, v58
	s_waitcnt vmcnt(0)
	s_nop 0
	v_cndmask_b32_e32 v11, v34, v14, vcc
	v_cndmask_b32_e32 v13, v37, v37, vcc
	v_cndmask_b32_e32 v14, v36, v36, vcc
	v_cndmask_b32_e32 v15, v35, v35, vcc
	v_cmp_lt_i32_e32 vcc, v7, v58
	s_nop 1
	v_cndmask_b32_e32 v0, v0, v22, vcc
	v_cndmask_b32_e32 v2, v2, v25, vcc
	v_cndmask_b32_e32 v1, v1, v24, vcc
	v_cndmask_b32_e32 v7, 0, v23, vcc
	v_cmp_le_i32_e32 vcc, v8, v58
	s_nop 1
	v_cndmask_b32_e32 v8, 0, v15, vcc
	v_cmp_le_i32_e32 vcc, v9, v58
	s_nop 1
	v_cndmask_b32_e32 v9, 0, v14, vcc
	v_cmp_le_i32_e32 vcc, v10, v58
	s_nop 1
	v_cndmask_b32_e32 v10, 0, v13, vcc
	v_cmp_le_i32_e32 vcc, v5, v58
	s_nop 1
	v_cndmask_b32_e32 v1, 0, v1, vcc
	v_cmp_le_i32_e32 vcc, v6, v58
	s_nop 1
	v_cvt_pk_bf16_f32 v6, v0, v7
	v_lshl_add_u32 v0, v40, 4, 16
	v_mad_u32_u24 v47, v4, s24, v0
	v_cndmask_b32_e32 v2, 0, v2, vcc
	s_nop 1
	v_cvt_pk_bf16_f32 v7, v1, v2
	s_nop 1
	v_cvt_pk_bf16_f32 v8, v11, v8
	s_nop 1
	v_cvt_pk_bf16_f32 v9, v9, v10
	ds_write_b128 v12, v[6:9] offset:34816
	s_waitcnt lgkmcnt(0)
	s_barrier
	global_load_dwordx2 v[26:27], v[26:27], off
	s_nop 0
	global_load_dword v28, v46, s[48:49]
	v_mov_b32_e32 v1, v21
	v_bfi_b32 v2, -16, v41, v3
	v_mad_u64_u32 v[2:3], s[4:5], v2, s24, v[0:1]
	ds_read_b128 v[4:7], v2
	ds_read_b128 v[22:25], v47 offset:34816
	s_waitcnt lgkmcnt(0)
	v_mfma_f32_16x16x32_bf16 v[22:25], v[4:7], v[22:25], 0
	v_or_b32_e32 v0, 0x4000, v20
	v_lshl_add_u64 v[0:1], v[16:17], 0, v[0:1]
	v_lshlrev_b64 v[34:35], 1, v[0:1]
	v_lshl_add_u64 v[36:37], s[54:55], 0, v[34:35]
	ds_read_b128 v[12:15], v2 offset:64
	ds_read_b128 v[8:11], v2 offset:128
	ds_read_b128 v[0:3], v2 offset:192
	v_lshl_add_u64 v[34:35], s[74:75], 0, v[34:35]
	s_mov_b64 s[4:5], 0
	s_waitcnt vmcnt(1)
	v_lshlrev_b32_e32 v38, 16, v26
	s_waitcnt vmcnt(0)
	v_add_f32_e32 v22, v22, v28
	v_and_b32_e32 v26, 0xffff0000, v26
	v_add_f32_e32 v23, v23, v28
	v_lshlrev_b32_e32 v39, 16, v27
	v_add_f32_e32 v24, v24, v28
	v_and_b32_e32 v27, 0xffff0000, v27
	v_add_f32_e32 v25, v25, v28
	v_mul_f32_e32 v22, v22, v38
	v_mul_f32_e32 v23, v23, v26
	v_mul_f32_e32 v24, v24, v39
	v_mul_f32_e32 v25, v25, v27
	s_nop 1
	v_cvt_pk_bf16_f32 v22, v22, v23
	s_nop 1
	v_cvt_pk_bf16_f32 v23, v24, v25
	global_store_dwordx2 v[18:19], v[22:23], off
	global_load_dwordx2 v[18:19], v[36:37], off
	s_nop 0
	global_load_dword v28, v46, s[48:49] offset:64
	ds_read_b128 v[22:25], v47 offset:39168
	s_waitcnt lgkmcnt(0)
	v_mfma_f32_16x16x32_bf16 v[22:25], v[4:7], v[22:25], 0
	v_mov_b32_e32 v27, v21
	v_or_b32_e32 v26, 0x8000, v20
	v_lshl_add_u64 v[26:27], v[16:17], 0, v[26:27]
	v_lshlrev_b64 v[26:27], 1, v[26:27]
	v_lshl_add_u64 v[36:37], s[54:55], 0, v[26:27]
	v_lshl_add_u64 v[26:27], s[74:75], 0, v[26:27]
	s_waitcnt vmcnt(1)
	v_lshlrev_b32_e32 v38, 16, v18
	v_and_b32_e32 v18, 0xffff0000, v18
	s_waitcnt vmcnt(0)
	v_add_f32_e32 v23, v23, v28
	v_lshlrev_b32_e32 v39, 16, v19
	v_and_b32_e32 v19, 0xffff0000, v19
	v_add_f32_e32 v25, v25, v28
	v_add_f32_e32 v22, v22, v28
	v_add_f32_e32 v24, v24, v28
	v_mul_f32_e32 v18, v23, v18
	v_mul_f32_e32 v19, v25, v19
	v_mul_f32_e32 v22, v22, v38
	v_mul_f32_e32 v23, v24, v39
	s_nop 1
	v_cvt_pk_bf16_f32 v18, v22, v18
	s_nop 1
	v_cvt_pk_bf16_f32 v19, v23, v19
	global_store_dwordx2 v[34:35], v[18:19], off
	global_load_dwordx2 v[18:19], v[36:37], off
	s_nop 0
	global_load_dword v28, v46, s[48:49] offset:128
	ds_read_b128 v[22:25], v47 offset:43520
	v_mov_b32_e32 v35, v21
	v_or_b32_e32 v34, 0xc000, v20
	v_lshl_add_u64 v[38:39], v[16:17], 0, v[34:35]
	ds_read_b128 v[34:37], v47 offset:43584
	s_waitcnt lgkmcnt(1)
	v_mfma_f32_16x16x32_bf16 v[22:25], v[4:7], v[22:25], 0
	v_lshlrev_b64 v[38:39], 1, v[38:39]
	v_lshl_add_u64 v[40:41], s[54:55], 0, v[38:39]
	v_lshl_add_u64 v[38:39], s[74:75], 0, v[38:39]
	s_waitcnt lgkmcnt(0)
	v_mfma_f32_16x16x32_bf16 v[22:25], v[12:15], v[34:37], v[22:25]
	s_waitcnt vmcnt(1)
	v_lshlrev_b32_e32 v34, 16, v18
	v_and_b32_e32 v18, 0xffff0000, v18
	s_waitcnt vmcnt(0)
	s_nop 3
	v_add_f32_e32 v23, v23, v28
	v_lshlrev_b32_e32 v35, 16, v19
	v_and_b32_e32 v19, 0xffff0000, v19
	v_add_f32_e32 v25, v25, v28
	v_add_f32_e32 v22, v22, v28
	v_add_f32_e32 v24, v24, v28
	v_mul_f32_e32 v18, v23, v18
	v_mul_f32_e32 v19, v25, v19
	v_mul_f32_e32 v22, v22, v34
	v_mul_f32_e32 v23, v24, v35
	s_nop 1
	v_cvt_pk_bf16_f32 v18, v22, v18
	s_nop 1
	v_cvt_pk_bf16_f32 v19, v23, v19
	global_store_dwordx2 v[26:27], v[18:19], off
	global_load_dwordx2 v[18:19], v[40:41], off
	s_nop 0
	global_load_dword v28, v46, s[48:49] offset:192
	ds_read_b128 v[22:25], v47 offset:47872
	ds_read_b128 v[34:37], v47 offset:47936
	s_waitcnt lgkmcnt(1)
	v_mfma_f32_16x16x32_bf16 v[22:25], v[4:7], v[22:25], 0
	v_mov_b32_e32 v27, v21
	v_or_b32_e32 v26, 0x10000, v20
	v_lshl_add_u64 v[26:27], v[16:17], 0, v[26:27]
	s_waitcnt lgkmcnt(0)
	v_mfma_f32_16x16x32_bf16 v[22:25], v[12:15], v[34:37], v[22:25]
	v_lshlrev_b64 v[26:27], 1, v[26:27]
	v_lshl_add_u64 v[40:41], s[54:55], 0, v[26:27]
	v_lshl_add_u64 v[26:27], s[74:75], 0, v[26:27]
	s_waitcnt vmcnt(1)
	v_lshlrev_b32_e32 v34, 16, v18
	v_and_b32_e32 v18, 0xffff0000, v18
	s_waitcnt vmcnt(0)
	s_nop 0
	v_add_f32_e32 v23, v23, v28
	v_lshlrev_b32_e32 v35, 16, v19
	v_and_b32_e32 v19, 0xffff0000, v19
	v_add_f32_e32 v25, v25, v28
	v_add_f32_e32 v22, v22, v28
	v_add_f32_e32 v24, v24, v28
	v_mul_f32_e32 v18, v23, v18
	v_mul_f32_e32 v19, v25, v19
	v_mul_f32_e32 v22, v22, v34
	v_mul_f32_e32 v23, v24, v35
	s_nop 1
	v_cvt_pk_bf16_f32 v18, v22, v18
	s_nop 1
	v_cvt_pk_bf16_f32 v19, v23, v19
	global_store_dwordx2 v[38:39], v[18:19], off
	global_load_dwordx2 v[18:19], v[40:41], off
	s_nop 0
	global_load_dword v28, v46, s[48:49] offset:256
	ds_read_b128 v[22:25], v47 offset:52224
	ds_read_b128 v[34:37], v47 offset:52288
	s_waitcnt lgkmcnt(1)
	v_mfma_f32_16x16x32_bf16 v[22:25], v[4:7], v[22:25], 0
	ds_read_b128 v[38:41], v47 offset:52352
	s_waitcnt lgkmcnt(1)
	v_mfma_f32_16x16x32_bf16 v[22:25], v[12:15], v[34:37], v[22:25]
	v_lshl_add_u64 v[34:35], v[16:17], 0, v[42:43]
	v_lshlrev_b64 v[42:43], 1, v[34:35]
	s_waitcnt vmcnt(1)
	v_lshlrev_b32_e32 v34, 16, v18
	s_waitcnt lgkmcnt(0)
	v_mfma_f32_16x16x32_bf16 v[22:25], v[8:11], v[38:41], v[22:25]
	v_and_b32_e32 v18, 0xffff0000, v18
	v_lshlrev_b32_e32 v35, 16, v19
	v_and_b32_e32 v19, 0xffff0000, v19
	v_lshl_add_u64 v[38:39], s[54:55], 0, v[42:43]
	v_lshl_add_u64 v[42:43], s[74:75], 0, v[42:43]
	s_waitcnt vmcnt(0)
	s_nop 1
	v_add_f32_e32 v23, v23, v28
	v_add_f32_e32 v25, v25, v28
	v_add_f32_e32 v22, v22, v28
	v_add_f32_e32 v24, v24, v28
	v_mul_f32_e32 v18, v23, v18
	v_mul_f32_e32 v19, v25, v19
	v_mul_f32_e32 v22, v22, v34
	v_mul_f32_e32 v23, v24, v35
	s_nop 1
	v_cvt_pk_bf16_f32 v18, v22, v18
	s_nop 1
	v_cvt_pk_bf16_f32 v19, v23, v19
	global_store_dwordx2 v[26:27], v[18:19], off
	global_load_dword v26, v46, s[48:49] offset:320
	ds_read_b128 v[22:25], v47 offset:56576
	ds_read_b128 v[34:37], v47 offset:56640
	global_load_dwordx2 v[18:19], v[38:39], off
	s_waitcnt lgkmcnt(1)
	v_mfma_f32_16x16x32_bf16 v[22:25], v[4:7], v[22:25], 0
	v_mov_b32_e32 v27, v21
	s_waitcnt vmcnt(0)
	v_lshlrev_b32_e32 v28, 16, v18
	s_waitcnt lgkmcnt(0)
	v_mfma_f32_16x16x32_bf16 v[22:25], v[12:15], v[34:37], v[22:25]
	ds_read_b128 v[34:37], v47 offset:56704
	v_and_b32_e32 v18, 0xffff0000, v18
	s_waitcnt lgkmcnt(0)
	v_mfma_f32_16x16x32_bf16 v[22:25], v[8:11], v[34:37], v[22:25]
	v_lshlrev_b32_e32 v34, 16, v19
	v_and_b32_e32 v19, 0xffff0000, v19
	s_nop 5
	v_add_f32_e32 v22, v22, v26
	v_add_f32_e32 v23, v23, v26
	v_add_f32_e32 v24, v24, v26
	v_add_f32_e32 v25, v25, v26
	v_or_b32_e32 v26, 0x18000, v20
	v_lshl_add_u64 v[26:27], v[16:17], 0, v[26:27]
	v_mul_f32_e32 v18, v23, v18
	v_mul_f32_e32 v19, v25, v19
	v_lshlrev_b64 v[26:27], 1, v[26:27]
	v_mul_f32_e32 v22, v22, v28
	v_mul_f32_e32 v23, v24, v34
	s_nop 1
	v_cvt_pk_bf16_f32 v18, v22, v18
	s_nop 1
	v_cvt_pk_bf16_f32 v19, v23, v19
	v_lshl_add_u64 v[44:45], s[54:55], 0, v[26:27]
	global_store_dwordx2 v[42:43], v[18:19], off
	global_load_dwordx2 v[18:19], v[44:45], off
	ds_read_b128 v[22:25], v47 offset:60928
	ds_read_b128 v[34:37], v47 offset:60992
	global_load_dword v28, v46, s[48:49] offset:384
	s_waitcnt lgkmcnt(1)
	v_mfma_f32_16x16x32_bf16 v[22:25], v[4:7], v[22:25], 0
	ds_read_b128 v[38:41], v47 offset:61056
	v_or_b32_e32 v20, 0x1c000, v20
	v_lshl_add_u64 v[16:17], v[16:17], 0, v[20:21]
	s_waitcnt lgkmcnt(1)
	v_mfma_f32_16x16x32_bf16 v[22:25], v[12:15], v[34:37], v[22:25]
	ds_read_b128 v[34:37], v47 offset:61120
	v_lshl_add_u64 v[26:27], s[74:75], 0, v[26:27]
	s_waitcnt lgkmcnt(1)
	v_mfma_f32_16x16x32_bf16 v[22:25], v[8:11], v[38:41], v[22:25]
	s_waitcnt lgkmcnt(0)
	v_mfma_f32_16x16x32_bf16 v[22:25], v[0:3], v[34:37], v[22:25]
	v_lshlrev_b64 v[36:37], 1, v[16:17]
	v_lshl_add_u64 v[38:39], s[54:55], 0, v[36:37]
	s_waitcnt vmcnt(1)
	v_lshlrev_b32_e32 v34, 16, v18
	v_and_b32_e32 v18, 0xffff0000, v18
	v_lshlrev_b32_e32 v35, 16, v19
	s_waitcnt vmcnt(0)
	s_nop 0
	v_add_f32_e32 v22, v22, v28
	v_add_f32_e32 v23, v23, v28
	v_add_f32_e32 v24, v24, v28
	v_and_b32_e32 v19, 0xffff0000, v19
	v_add_f32_e32 v25, v25, v28
	v_mul_f32_e32 v22, v22, v34
	v_mul_f32_e32 v18, v23, v18
	v_mul_f32_e32 v23, v24, v35
	v_mul_f32_e32 v19, v25, v19
	s_nop 1
	v_cvt_pk_bf16_f32 v34, v22, v18
	s_nop 1
	v_cvt_pk_bf16_f32 v35, v23, v19
	ds_read_b128 v[22:25], v47 offset:65280
	ds_read_b128 v[16:19], v47 offset:65344
	s_waitcnt lgkmcnt(1)
	v_mfma_f32_16x16x32_bf16 v[4:7], v[4:7], v[22:25], 0
	ds_read_b128 v[22:25], v47 offset:65408
	global_store_dwordx2 v[26:27], v[34:35], off
	s_waitcnt lgkmcnt(1)
	v_mfma_f32_16x16x32_bf16 v[4:7], v[12:15], v[16:19], v[4:7]
	ds_read_b128 v[12:15], v47 offset:65472
	global_load_dwordx2 v[16:17], v[38:39], off
	s_waitcnt lgkmcnt(1)
	v_mfma_f32_16x16x32_bf16 v[4:7], v[8:11], v[22:25], v[4:7]
	global_load_dword v10, v46, s[48:49] offset:448
	v_lshl_add_u64 v[8:9], s[74:75], 0, v[36:37]
	s_waitcnt lgkmcnt(0)
	v_mfma_f32_16x16x32_bf16 v[0:3], v[0:3], v[12:15], v[4:7]
	s_waitcnt vmcnt(1)
	s_nop 2
	v_lshlrev_b32_e32 v4, 16, v16
	v_and_b32_e32 v5, 0xffff0000, v16
	v_lshlrev_b32_e32 v6, 16, v17
	s_waitcnt vmcnt(0)
	v_add_f32_e32 v0, v0, v10
	v_add_f32_e32 v1, v1, v10
	v_add_f32_e32 v2, v2, v10
	v_and_b32_e32 v7, 0xffff0000, v17
	v_add_f32_e32 v3, v3, v10
	v_mul_f32_e32 v0, v0, v4
	v_mul_f32_e32 v1, v1, v5
	v_mul_f32_e32 v2, v2, v6
	v_mul_f32_e32 v3, v3, v7
	s_nop 1
	v_cvt_pk_bf16_f32 v0, v0, v1
	s_nop 1
	v_cvt_pk_bf16_f32 v1, v2, v3
	global_store_dwordx2 v[8:9], v[0:1], off
	s_barrier
.LBB0_423:
	s_andn2_b64 vcc, exec, s[4:5]
	s_cbranch_vccnz .LBB0_420
	s_bfe_u32 s30, s29, 0x40002
	s_waitcnt vmcnt(0)
	v_mov_b32_e32 v69, v183
	s_lshl_b32 s8, s29, 5
	s_and_b32 s4, s8, 0xfffff800
	s_lshl_b32 s5, s30, 7
	v_bfe_u32 v71, v69, 6, 1
	v_and_b32_e32 v70, 15, v69
	s_or_b32 s10, s5, s4
	v_lshlrev_b32_e32 v73, 6, v71
	s_and_b32 s6, s29, 3
	v_ashrrev_i32_e32 v72, 7, v69
	v_or3_b32 v0, v73, s10, v70
	v_lshl_add_u32 v24, s6, 2, v72
	v_ashrrev_i32_e32 v1, 31, v0
	v_lshlrev_b64 v[0:1], 11, v[0:1]
	v_lshlrev_b32_e32 v22, 6, v24
	v_bfe_u32 v34, v69, 4, 2
	v_lshl_add_u64 v[0:1], s[2:3], 0, v[0:1]
	v_ashrrev_i32_e32 v23, 31, v22
	v_lshl_add_u64 v[0:1], v[22:23], 1, v[0:1]
	v_lshlrev_b32_e32 v20, 4, v34
	v_lshl_add_u64 v[0:1], v[0:1], 0, v[20:21]
	global_load_dwordx4 v[8:11], v[0:1], off
	global_load_dwordx4 v[12:15], v[0:1], off offset:64
	v_and_b32_e32 v6, 7, v69
	s_cmp_lg_u32 s30, 0
	v_ashrrev_i32_e32 v1, 3, v69
	s_cselect_b64 s[4:5], -1, 0
	v_lshlrev_b32_e32 v2, 3, v6
	v_cmp_lt_i32_e32 vcc, s25, v1
	v_mov_b32_e32 v16, 0
	s_addk_i32 s10, 0xff80
	s_lshl_b32 s9, s6, 6
	s_or_b64 s[12:13], s[4:5], vcc
	v_mov_b32_e32 v0, 0
	v_lshlrev_b32_e32 v26, 1, v2
	v_mov_b32_e32 v2, 0
	v_mov_b32_e32 v3, 0
	v_mov_b32_e32 v4, 0
	v_mov_b32_e32 v5, 0
	v_mov_b32_e32 v17, v16
	v_mov_b32_e32 v18, v16
	v_mov_b32_e32 v19, v16
	s_lshl_b32 s76, s9, 1
	v_mov_b32_e32 v128, v1
	v_add_u32_e32 v2, s10, v1
	v_ashrrev_i32_e32 v3, 31, v2
	v_lshlrev_b64 v[2:3], 9, v[2:3]
	v_lshl_add_u64 v[4:5], s[16:17], 0, v[2:3]
	v_lshl_add_u64 v[2:3], s[34:35], 0, v[2:3]
	v_lshl_add_u64 v[4:5], v[4:5], 0, s[76:77]
	v_lshl_add_u64 v[2:3], v[2:3], 0, s[76:77]
	v_mov_b32_e32 v27, v21
	v_lshl_add_u64 v[4:5], v[4:5], 0, v[26:27]
	v_lshl_add_u64 v[2:3], v[2:3], 0, v[26:27]
	s_mov_b32 s12, 0x8000
	s_mov_b32 s13, 0
	v_lshl_add_u64 v[130:131], v[4:5], 0, s[12:13]
	v_lshl_add_u64 v[132:133], v[2:3], 0, s[12:13]
	v_lshl_add_u64 v[134:135], v[130:131], 0, s[12:13]
	v_lshl_add_u64 v[136:137], v[132:133], 0, s[12:13]
	v_lshl_add_u64 v[138:139], v[134:135], 0, s[12:13]
	v_lshl_add_u64 v[140:141], v[136:137], 0, s[12:13]
	global_load_dwordx4 v[150:153], v[134:135], off
	global_load_dwordx4 v[154:157], v[136:137], off
	global_load_dwordx4 v[158:161], v[138:139], off
	global_load_dwordx4 v[162:165], v[140:141], off
	v_mov_b32_e32 v16, 0
	v_mov_b32_e32 v17, 0
	v_mov_b32_e32 v18, 0
	v_mov_b32_e32 v19, 0
	v_mov_b32_e32 v142, 0
	v_mov_b32_e32 v143, 0
	v_mov_b32_e32 v144, 0
	v_mov_b32_e32 v145, 0
	v_mov_b32_e32 v146, 0
	v_mov_b32_e32 v147, 0
	v_mov_b32_e32 v148, 0
	v_mov_b32_e32 v149, 0
	v_mov_b32_e32 v166, 0
	v_mov_b32_e32 v167, 0
	v_mov_b32_e32 v168, 0
	v_mov_b32_e32 v169, 0
	s_and_saveexec_b64 s[6:7], s[4:5]
	s_cbranch_execz .Lattn_stg_skip_L0
	global_load_dwordx4 v[16:19], v[4:5], off
	global_load_dwordx4 v[142:145], v[2:3], off
	global_load_dwordx4 v[146:149], v[130:131], off
	global_load_dwordx4 v[166:169], v[132:133], off
.Lattn_stg_skip_L0:
	s_or_b64 exec, exec, s[6:7]
	v_lshl_add_u32 v28, v6, 4, 16
	s_movk_i32 s6, 0x1070
	v_mad_u32_u24 v25, v6, s6, v28
	v_mad_u32_u24 v0, v128, s26, v28
	v_lshl_add_u32 v1, v128, 1, v25
	s_waitcnt vmcnt(0)
	ds_write_b128 v0, v[16:19]
	ds_write_b128 v0, v[146:149] offset:9216
	ds_write_b128 v0, v[150:153] offset:18432
	ds_write_b128 v0, v[158:161] offset:27648
	ds_write_b16 v1, v142 offset:36864
	ds_write_b16_d16_hi v1, v142 offset:37392
	ds_write_b16 v1, v143 offset:37920
	ds_write_b16_d16_hi v1, v143 offset:38448
	ds_write_b16 v1, v144 offset:38976
	ds_write_b16_d16_hi v1, v144 offset:39504
	ds_write_b16 v1, v145 offset:40032
	ds_write_b16_d16_hi v1, v145 offset:40560
	ds_write_b16 v1, v166 offset:36992
	ds_write_b16_d16_hi v1, v166 offset:37520
	ds_write_b16 v1, v167 offset:38048
	ds_write_b16_d16_hi v1, v167 offset:38576
	ds_write_b16 v1, v168 offset:39104
	ds_write_b16_d16_hi v1, v168 offset:39632
	ds_write_b16 v1, v169 offset:40160
	ds_write_b16_d16_hi v1, v169 offset:40688
	ds_write_b16 v1, v154 offset:37120
	ds_write_b16_d16_hi v1, v154 offset:37648
	ds_write_b16 v1, v155 offset:38176
	ds_write_b16_d16_hi v1, v155 offset:38704
	ds_write_b16 v1, v156 offset:39232
	ds_write_b16_d16_hi v1, v156 offset:39760
	ds_write_b16 v1, v157 offset:40288
	ds_write_b16_d16_hi v1, v157 offset:40816
	ds_write_b16 v1, v162 offset:37248
	ds_write_b16_d16_hi v1, v162 offset:37776
	ds_write_b16 v1, v163 offset:38304
	ds_write_b16_d16_hi v1, v163 offset:38832
	ds_write_b16 v1, v164 offset:39360
	ds_write_b16_d16_hi v1, v164 offset:39888
	ds_write_b16 v1, v165 offset:40416
	ds_write_b16_d16_hi v1, v165 offset:40944
	v_add_u32_e32 v1, 1, v24
	v_cvt_f32_i32_e32 v1, v1
	v_mul_f32_e32 v0, -0.5, v1
	s_mov_b32 s4, 0xc2fc0000
	v_cmp_gt_f32_e32 vcc, s4, v0
	v_readlane_b32 s36, v254, 30
	v_ashrrev_i32_e32 v25, 31, v24
	v_cndmask_b32_e32 v0, 0, v30, vcc
	v_fmac_f32_e32 v0, -0.5, v1
	v_exp_f32_e32 v0, v0
	v_cndmask_b32_e32 v1, 0, v31, vcc
	v_readlane_b32 s40, v254, 34
	v_readlane_b32 s41, v254, 35
	v_ldexp_f32 v2, v0, v1
	s_waitcnt lgkmcnt(0)
	v_lshl_add_u64 v[0:1], v[24:25], 2, s[40:41]
	s_barrier
	global_load_dword v24, v[0:1], off
	v_lshlrev_b32_e32 v0, 2, v34
	v_sub_u32_e32 v0, v70, v0
	v_add_u32_e32 v3, -1, v0
	v_cvt_f32_i32_e32 v3, v3
	v_cvt_f32_i32_e32 v1, v0
	v_add_u32_e32 v4, -2, v0
	v_add_u32_e32 v5, -3, v0
	v_mul_f32_e64 v26, -v2, v3
	v_and_b32_e32 v3, 64, v32
	v_mul_f32_e64 v25, v1, -v2
	v_xor_b32_e32 v1, 16, v32
	v_add_u32_e32 v3, 64, v3
	v_cmp_lt_i32_e32 vcc, v1, v3
	s_and_b32 s31, s14, 0xfffff800
	s_and_b32 s33, s8, 0x780
	v_cndmask_b32_e32 v1, v32, v1, vcc
	v_lshlrev_b32_e32 v35, 2, v1
	v_xor_b32_e32 v1, 32, v32
	s_and_b32 s56, s28, 3
	v_cvt_f32_i32_e32 v4, v4
	v_cvt_f32_i32_e32 v5, v5
	v_cmp_lt_i32_e32 vcc, v1, v3
	s_cmp_eq_u32 s30, 0
	v_lshlrev_b32_e32 v74, 3, v34
	v_cndmask_b32_e32 v1, v32, v1, vcc
	s_cselect_b64 s[4:5], -1, 0
	v_lshlrev_b32_e32 v36, 2, v1
	v_cmp_gt_i32_e64 s[6:7], 0, v0
	v_cmp_gt_i32_e64 s[8:9], 1, v0
	v_cmp_gt_i32_e64 s[10:11], 2, v0
	v_cmp_gt_i32_e64 s[12:13], 3, v0
	v_lshl_add_u64 v[0:1], v[22:23], 1, s[52:53]
	v_mov_b32_e32 v75, v21
	s_or_b32 s31, s31, s33
	v_lshl_add_u64 v[16:17], v[0:1], 0, v[74:75]
	v_or_b32_e32 v0, s31, v73
	v_mul_f32_e64 v27, -v2, v4
	v_mul_f32_e64 v28, -v2, v5
	v_add_u32_e32 v18, v0, v70
	v_fmamk_f32 v37, v2, 0xc3000000, v25
	v_fmamk_f32 v38, v2, 0xc3000000, v26
	v_fmamk_f32 v39, v2, 0xc3000000, v27
	v_fmamk_f32 v40, v2, 0xc3000000, v28
	v_fmamk_f32 v41, v2, 0xc2e00000, v25
	v_fmamk_f32 v42, v2, 0xc2e00000, v26
	v_fmamk_f32 v43, v2, 0xc2e00000, v27
	v_fmamk_f32 v44, v2, 0xc2e00000, v28
	v_fmamk_f32 v45, v2, 0xc2c00000, v25
	v_fmamk_f32 v46, v2, 0xc2c00000, v26
	v_fmamk_f32 v47, v2, 0xc2c00000, v27
	v_fmamk_f32 v48, v2, 0xc2c00000, v28
	v_fmamk_f32 v49, v2, 0xc2a00000, v25
	v_fmamk_f32 v50, v2, 0xc2a00000, v26
	v_fmamk_f32 v51, v2, 0xc2a00000, v27
	v_fmamk_f32 v52, v2, 0xc2a00000, v28
	v_fmamk_f32 v53, v2, 0xc2800000, v25
	v_fmamk_f32 v54, v2, 0xc2800000, v26
	v_fmamk_f32 v55, v2, 0xc2800000, v27
	v_fmamk_f32 v56, v2, 0xc2800000, v28
	v_fmamk_f32 v57, v2, 0xc2400000, v25
	v_fmamk_f32 v58, v2, 0xc2400000, v26
	v_fmamk_f32 v59, v2, 0xc2400000, v27
	v_fmamk_f32 v60, v2, 0xc2400000, v28
	v_fmamk_f32 v61, v2, 0xc2000000, v25
	v_fmamk_f32 v62, v2, 0xc2000000, v26
	v_fmamk_f32 v63, v2, 0xc2000000, v27
	v_fmamk_f32 v64, v2, 0xc2000000, v28
	v_fmamk_f32 v65, v2, 0xc1800000, v25
	v_fmamk_f32 v66, v2, 0xc1800000, v26
	v_fmamk_f32 v67, v2, 0xc1800000, v27
	v_fmamk_f32 v68, v2, 0xc1800000, v28
	v_fmac_f32_e32 v25, 0x80000000, v2
	v_fmac_f32_e32 v26, 0x80000000, v2
	v_fmac_f32_e32 v27, 0x80000000, v2
	v_fmac_f32_e32 v28, 0x80000000, v2
	v_ashrrev_i32_e32 v19, 31, v18
	v_lshlrev_b32_e32 v2, 6, v72
	v_lshlrev_b64 v[0:1], 11, v[18:19]
	v_lshl_add_u32 v2, s56, 8, v2
	v_and_or_b32 v0, v69, 48, v0
	v_ashrrev_i32_e32 v3, 31, v2
	v_lshl_add_u64 v[0:1], v[2:3], 1, v[0:1]
	v_lshl_add_u64 v[22:23], s[0:1], 0, v[0:1]
	v_lshlrev_b32_e32 v0, 7, v71
	s_movk_i32 s31, 0x210
	v_mad_u32_u24 v0, v70, s31, v0
	v_add3_u32 v69, v0, v74, s27
	v_mul_u32_u24_e32 v0, 0x90, v70
	s_movk_i32 s31, 0x2400
	v_mad_u32_u24 v0, v71, s31, v0
	v_add3_u32 v19, v0, v20, 16
	v_mov_b64_e32 v[0:1], v[12:13]
	v_mov_b64_e32 v[4:5], v[8:9]
	v_lshlrev_b32_e32 v34, 2, v71
	s_mov_b64 s[78:79], 0
	v_mov_b64_e32 v[2:3], v[14:15]
	v_mov_b64_e32 v[6:7], v[10:11]
	v_readlane_b32 s37, v254, 31
	v_readlane_b32 s38, v254, 32
	v_readlane_b32 s39, v254, 33
	v_readlane_b32 s42, v254, 36
	v_readlane_b32 s43, v254, 37
	v_readlane_b32 s44, v254, 38
	v_readlane_b32 s45, v254, 39
	v_readlane_b32 s46, v254, 40
	v_readlane_b32 s47, v254, 41
	v_readlane_b32 s48, v254, 42
	v_readlane_b32 s49, v254, 43
	v_readlane_b32 s50, v254, 44
	v_readlane_b32 s51, v254, 45
	s_branch .LBB0_434

.LBB0_1356:
	s_cmpk_gt_i32 s58, 0xff
	s_mov_b64 s[2:3], -1
	s_cbranch_scc0 .LBB0_1358
	s_lshl_b32 s2, s58, 4
	v_mov_b32_e32 v3, v183
	s_and_b32 s10, s2, 0x7fffff80
	s_addk_i32 s10, 0xf000
	v_ashrrev_i32_e32 v28, 4, v3
	v_add_u32_e32 v0, s10, v28
	v_ashrrev_i32_e32 v1, 31, v0
	v_lshlrev_b64 v[4:5], 6, v[0:1]
	v_lshl_add_u64 v[4:5], s[0:1], 0, v[4:5]
	global_load_dwordx4 v[6:9], v[4:5], off offset:32
	global_load_dwordx4 v[10:13], v[4:5], off offset:16
	global_load_dwordx4 v[14:17], v[4:5], off offset:48
	global_load_dwordx4 v[22:25], v[4:5], off
	v_mov_b32_e32 v178, 0x800
	v_mov_b32_e32 v179, 0
	v_lshl_add_u64 v[176:177], v[4:5], 0, v[178:179]
	global_load_dwordx4 v[128:131], v[176:177], off
	global_load_dwordx4 v[132:135], v[176:177], off offset:16
	global_load_dwordx4 v[136:139], v[176:177], off offset:32
	global_load_dwordx4 v[140:143], v[176:177], off offset:48
	v_lshl_add_u64 v[176:177], v[176:177], 0, v[178:179]
	global_load_dwordx4 v[144:147], v[176:177], off
	global_load_dwordx4 v[148:151], v[176:177], off offset:16
	global_load_dwordx4 v[152:155], v[176:177], off offset:32
	global_load_dwordx4 v[156:159], v[176:177], off offset:48
	v_lshl_add_u64 v[176:177], v[176:177], 0, v[178:179]
	global_load_dwordx4 v[160:163], v[176:177], off
	global_load_dwordx4 v[164:167], v[176:177], off offset:16
	global_load_dwordx4 v[168:171], v[176:177], off offset:32
	global_load_dwordx4 v[172:175], v[176:177], off offset:48
	s_and_b32 s8, s58, 7
	v_lshlrev_b64 v[0:1], 11, v[0:1]
	s_lshl_b32 s48, s8, 8
	v_and_b32_e32 v4, 15, v3
	v_lshl_add_u64 v[0:1], s[34:35], 0, v[0:1]
	v_lshlrev_b32_e32 v20, 4, v4
	v_lshl_add_u64 v[0:1], v[0:1], 0, s[48:49]
	v_lshl_add_u64 v[0:1], v[0:1], 0, v[20:21]
	s_lshl_b32 s11, s8, 7
	s_lshl_b32 s2, s8, 9
	global_load_dwordx4 v[34:37], v[0:1], off
	v_mov_b32_e32 v178, 0x10000
	v_lshl_add_u64 v[176:177], v[0:1], 0, v[178:179]
	global_load_dwordx4 v[188:191], v[176:177], off
	v_lshl_add_u64 v[176:177], v[176:177], 0, v[178:179]
	global_load_dwordx4 v[192:195], v[176:177], off
	v_lshl_add_u64 v[176:177], v[176:177], 0, v[178:179]
	global_load_dwordx4 v[196:199], v[176:177], off
	s_add_u32 s2, s38, s2
	v_lshlrev_b32_e32 v0, 5, v4
	s_addc_u32 s3, s39, 0
	global_load_dwordx4 v[38:41], v0, s[2:3]
	global_load_dwordx4 v[42:45], v0, s[2:3] offset:16
	s_lshl_b32 s8, s8, 16
	v_lshlrev_b32_e32 v18, 7, v28
	s_add_u32 s8, s44, s8
	v_ashrrev_i32_e32 v19, 31, v18
	s_addc_u32 s9, s45, 0
	v_mov_b32_e32 v1, v21
	v_lshl_add_u64 v[18:19], v[18:19], 2, s[8:9]
	v_lshl_add_u64 v[18:19], v[18:19], 0, v[0:1]
	global_load_dwordx4 v[208:211], v[18:19], off
	global_load_dwordx4 v[212:215], v[18:19], off offset:16
	v_mov_b32_e32 v178, 0x4000
	v_lshl_add_u64 v[176:177], v[18:19], 0, v[178:179]
	global_load_dwordx4 v[216:219], v[176:177], off
	global_load_dwordx4 v[220:223], v[176:177], off offset:16
	v_lshl_add_u64 v[176:177], v[176:177], 0, v[178:179]
	global_load_dwordx4 v[224:227], v[176:177], off
	global_load_dwordx4 v[228:231], v[176:177], off offset:16
	v_lshl_add_u64 v[176:177], v[176:177], 0, v[178:179]
	global_load_dwordx4 v[232:235], v[176:177], off
	global_load_dwordx4 v[236:239], v[176:177], off offset:16
	s_movk_i32 s12, 0x880
	s_waitcnt vmcnt(0)
	v_mov_b32_e32 v200, v38
	v_mov_b32_e32 v201, v39
	v_mov_b32_e32 v202, v40
	v_mov_b32_e32 v203, v41
	v_mov_b32_e32 v204, v42
	v_mov_b32_e32 v205, v43
	v_mov_b32_e32 v206, v44
	v_mov_b32_e32 v207, v45
	v_mov_b32_e32 v27, v6
	v_mov_b32_e32 v47, v8
	v_mov_b32_e32 v48, v10
	v_mov_b32_e32 v49, v14
	v_mov_b32_e32 v14, v11
	v_mov_b32_e32 v10, v12
	v_mov_b32_e32 v11, v16
	v_mov_b32_e32 v16, v13
	v_mov_b32_e32 v26, v22
	v_mov_b32_e32 v6, v23
	v_mov_b32_e32 v46, v24
	v_mov_b32_e32 v8, v25
	v_pk_add_f32 v[12:13], v[48:49], v[14:15]
	v_pk_add_f32 v[10:11], v[10:11], v[16:17]
	v_pk_add_f32 v[6:7], v[26:27], v[6:7]
	v_pk_add_f32 v[8:9], v[46:47], v[8:9]
	v_pk_add_f32 v[10:11], v[12:13], v[10:11]
	v_pk_add_f32 v[6:7], v[6:7], v[8:9]
	v_lshlrev_b32_e32 v12, 16, v34
	v_pk_add_f32 v[6:7], v[6:7], v[10:11]
	v_and_b32_e32 v13, 0xffff0000, v34
	v_add_f32_e32 v2, v6, v7
	v_fmamk_f32 v2, v2, 0x3a800000, v29
	v_mul_f32_e32 v5, 0x4b800000, v2
	v_cmp_gt_f32_e32 vcc, s25, v2
	v_lshlrev_b32_e32 v16, 16, v36
	v_and_b32_e32 v17, 0xffff0000, v36
	v_cndmask_b32_e32 v2, v2, v5, vcc
	v_rsq_f32_e32 v2, v2
	v_lshlrev_b32_e32 v14, 16, v35
	v_and_b32_e32 v15, 0xffff0000, v35
	v_lshlrev_b32_e32 v6, 16, v37
	v_mul_f32_e32 v5, 0x45800000, v2
	v_cndmask_b32_e32 v2, v2, v5, vcc
	v_and_b32_e32 v7, 0xffff0000, v37
	v_pk_mul_f32 v[8:9], v[2:3], v[12:13] op_sel_hi:[0,1]
	v_pk_mul_f32 v[12:13], v[2:3], v[16:17] op_sel_hi:[0,1]
	v_pk_mul_f32 v[10:11], v[2:3], v[14:15] op_sel_hi:[0,1]
	v_pk_mul_f32 v[6:7], v[2:3], v[6:7] op_sel_hi:[0,1]
	v_pk_mul_f32 v[12:13], v[42:43], v[12:13]
	v_pk_mul_f32 v[10:11], v[40:41], v[10:11]
	v_pk_mul_f32 v[8:9], v[38:39], v[8:9]
	v_pk_mul_f32 v[6:7], v[44:45], v[6:7]
	s_nop 1
	v_cvt_pk_bf16_f32 v36, v8, v9
	s_nop 1
	v_cvt_pk_bf16_f32 v37, v10, v11
	s_nop 1
	v_cvt_pk_bf16_f32 v13, v12, v13
	v_mad_u32_u24 v12, v4, s12, 16
	s_nop 1
	v_cvt_pk_bf16_f32 v38, v6, v7
	v_mov_b32_e32 v14, v208
	v_mov_b32_e32 v15, v209
	v_mov_b32_e32 v16, v210
	v_mov_b32_e32 v17, v211
	v_mov_b32_e32 v22, v212
	v_mov_b32_e32 v23, v213
	v_mov_b32_e32 v24, v214
	v_mov_b32_e32 v25, v215
	v_lshlrev_b32_e32 v7, 3, v4
	v_mov_b32_e32 v2, s49
	v_lshl_add_u32 v19, v28, 1, v12
	v_or_b32_e32 v11, 4, v7
	v_cmp_gt_i32_e32 vcc, v7, v28
	v_mov_b32_e32 v18, s49
	ds_write_b16 v19, v36
	ds_write_b16_d16_hi v19, v36 offset:272
	ds_write_b16 v19, v37 offset:544
	ds_write_b16_d16_hi v19, v37 offset:816
	ds_write_b16 v19, v13 offset:1088
	ds_write_b16_d16_hi v19, v13 offset:1360
	ds_write_b16 v19, v38 offset:1632
	ds_write_b16_d16_hi v19, v38 offset:1904
	v_or_b32_e32 v8, 5, v7
	v_add_u32_e32 v5, 0x200, v3
	v_or_b32_e32 v9, 6, v7
	v_ashrrev_i32_e32 v58, 4, v5
	v_or_b32_e32 v10, 7, v7
	v_or_b32_e32 v5, 2, v7
	v_add_u32_e32 v26, s10, v58
	v_or_b32_e32 v6, 3, v7
	v_ashrrev_i32_e32 v27, 31, v26
	v_lshlrev_b64 v[34:35], 6, v[26:27]
	v_lshl_add_u64 v[42:43], s[0:1], 0, v[34:35]
	s_movk_i32 s12, 0xf790
	s_waitcnt vmcnt(1)
	v_cndmask_b32_e32 v13, v16, v16, vcc
	v_cndmask_b32_e32 v19, v17, v17, vcc
	v_cndmask_b32_e32 v2, v14, v2, vcc
	v_cmp_gt_i32_e32 vcc, v11, v28
	s_waitcnt vmcnt(0)
	s_nop 0
	v_cndmask_b32_e32 v18, v22, v18, vcc
	v_cndmask_b32_e32 v22, v25, v25, vcc
	v_cndmask_b32_e32 v24, v24, v24, vcc
	v_cndmask_b32_e32 v23, v23, v23, vcc
	v_cmp_lt_i32_e32 vcc, v7, v28
	s_nop 1
	v_cndmask_b32_e32 v2, v2, v14, vcc
	v_cndmask_b32_e32 v14, v19, v17, vcc
	v_cndmask_b32_e32 v13, v13, v16, vcc
	v_cndmask_b32_e32 v15, 0, v15, vcc
	v_cmp_le_i32_e32 vcc, v8, v28
	s_nop 1
	v_cndmask_b32_e32 v16, 0, v23, vcc
	v_cmp_le_i32_e32 vcc, v9, v28
	s_nop 1
	v_cndmask_b32_e32 v17, 0, v24, vcc
	v_cmp_le_i32_e32 vcc, v10, v28
	s_nop 1
	v_cndmask_b32_e32 v19, 0, v22, vcc
	v_cmp_le_i32_e32 vcc, v5, v28
	s_nop 1
	v_cndmask_b32_e32 v13, 0, v13, vcc
	v_cmp_le_i32_e32 vcc, v6, v28
	s_nop 1
	v_cndmask_b32_e32 v22, 0, v14, vcc
	s_nop 1
	v_cvt_pk_bf16_f32 v14, v2, v15
	s_nop 1
	v_cvt_pk_bf16_f32 v15, v13, v22
	s_nop 1
	v_cvt_pk_bf16_f32 v16, v18, v16
	s_nop 1
	v_cvt_pk_bf16_f32 v17, v17, v19
	v_mov_b32_e32 v22, v128
	v_mov_b32_e32 v23, v129
	v_mov_b32_e32 v24, v130
	v_mov_b32_e32 v25, v131
	v_mov_b32_e32 v34, v136
	v_mov_b32_e32 v35, v137
	v_mov_b32_e32 v36, v138
	v_mov_b32_e32 v37, v139
	v_mov_b32_e32 v38, v132
	v_mov_b32_e32 v39, v133
	v_mov_b32_e32 v40, v134
	v_mov_b32_e32 v41, v135
	s_nop 0
	v_mov_b32_e32 v42, v140
	v_mov_b32_e32 v43, v141
	v_mov_b32_e32 v44, v142
	v_mov_b32_e32 v45, v143
	v_lshlrev_b64 v[18:19], 11, v[26:27]
	v_lshl_add_u64 v[18:19], s[34:35], 0, v[18:19]
	v_lshl_add_u64 v[18:19], v[18:19], 0, s[48:49]
	v_lshl_add_u64 v[18:19], v[18:19], 0, v[20:21]
	v_mov_b32_e32 v46, v188
	v_mov_b32_e32 v47, v189
	v_mov_b32_e32 v48, v190
	v_mov_b32_e32 v49, v191
	v_mov_b32_e32 v50, v200
	v_mov_b32_e32 v51, v201
	v_mov_b32_e32 v52, v202
	v_mov_b32_e32 v53, v203
	v_mov_b32_e32 v54, v204
	v_mov_b32_e32 v55, v205
	v_mov_b32_e32 v56, v206
	v_mov_b32_e32 v57, v207
	v_mad_i32_i24 v2, v4, s12, v12
	v_mad_u64_u32 v[26:27], s[12:13], v28, s33, v[2:3]
	ds_write_b128 v26, v[14:17] offset:34816
	v_lshlrev_b32_e32 v18, 7, v58
	v_ashrrev_i32_e32 v19, 31, v18
	v_lshl_add_u64 v[18:19], v[18:19], 2, s[8:9]
	v_lshl_add_u64 v[18:19], v[18:19], 0, v[0:1]
	s_waitcnt vmcnt(6)
	v_mov_b32_e32 v14, v22
	s_waitcnt vmcnt(5)
	v_mov_b32_e32 v15, v34
	v_mov_b32_e32 v34, v23
	v_mov_b32_e32 v16, v24
	v_mov_b32_e32 v17, v36
	v_mov_b32_e32 v36, v25
	s_waitcnt vmcnt(4)
	v_mov_b32_e32 v22, v38
	s_waitcnt vmcnt(3)
	v_mov_b32_e32 v23, v42
	v_mov_b32_e32 v42, v39
	v_mov_b32_e32 v24, v40
	v_mov_b32_e32 v25, v44
	v_mov_b32_e32 v44, v41
	v_pk_add_f32 v[14:15], v[14:15], v[34:35]
	v_pk_add_f32 v[16:17], v[16:17], v[36:37]
	v_pk_add_f32 v[22:23], v[22:23], v[42:43]
	v_pk_add_f32 v[24:25], v[24:25], v[44:45]
	v_pk_add_f32 v[14:15], v[14:15], v[16:17]
	v_pk_add_f32 v[16:17], v[22:23], v[24:25]
	s_waitcnt vmcnt(2)
	v_lshlrev_b32_e32 v26, 16, v46
	v_pk_add_f32 v[14:15], v[14:15], v[16:17]
	v_and_b32_e32 v27, 0xffff0000, v46
	v_add_f32_e32 v13, v14, v15
	v_fmamk_f32 v13, v13, 0x3a800000, v29
	v_mul_f32_e32 v14, 0x4b800000, v13
	v_cmp_gt_f32_e32 vcc, s25, v13
	v_lshlrev_b32_e32 v38, 16, v47
	v_and_b32_e32 v39, 0xffff0000, v47
	v_cndmask_b32_e32 v13, v13, v14, vcc
	v_rsq_f32_e32 v13, v13
	v_lshlrev_b32_e32 v40, 16, v48
	v_and_b32_e32 v41, 0xffff0000, v48
	v_lshlrev_b32_e32 v14, 16, v49
	v_mul_f32_e32 v16, 0x45800000, v13
	v_and_b32_e32 v15, 0xffff0000, v49
	v_cndmask_b32_e32 v16, v13, v16, vcc
	v_pk_mul_f32 v[22:23], v[16:17], v[26:27] op_sel_hi:[0,1]
	v_pk_mul_f32 v[24:25], v[16:17], v[38:39] op_sel_hi:[0,1]
	v_pk_mul_f32 v[26:27], v[16:17], v[40:41] op_sel_hi:[0,1]
	v_pk_mul_f32 v[14:15], v[16:17], v[14:15] op_sel_hi:[0,1]
	s_waitcnt vmcnt(1)
	v_pk_mul_f32 v[16:17], v[52:53], v[24:25]
	v_pk_mul_f32 v[22:23], v[50:51], v[22:23]
	s_waitcnt vmcnt(0)
	v_pk_mul_f32 v[14:15], v[56:57], v[14:15]
	v_pk_mul_f32 v[24:25], v[54:55], v[26:27]
	s_nop 1
	v_cvt_pk_bf16_f32 v13, v22, v23
	s_nop 1
	v_cvt_pk_bf16_f32 v27, v16, v17
	v_cmp_gt_i32_e32 vcc, v7, v58
	s_nop 1
	v_cvt_pk_bf16_f32 v28, v24, v25
	s_nop 1
	v_cvt_pk_bf16_f32 v36, v14, v15
	v_mov_b32_e32 v14, v216
	v_mov_b32_e32 v15, v217
	v_mov_b32_e32 v16, v218
	v_mov_b32_e32 v17, v219
	v_mov_b32_e32 v22, v220
	v_mov_b32_e32 v23, v221
	v_mov_b32_e32 v24, v222
	v_mov_b32_e32 v25, v223
	v_add_u32_e32 v19, 0x400, v3
	v_mov_b32_e32 v18, s49
	v_ashrrev_i32_e32 v59, 4, v19
	v_lshl_add_u32 v19, v58, 1, v12
	v_mov_b32_e32 v26, s49
	ds_write_b16 v19, v13
	ds_write_b16_d16_hi v19, v13 offset:272
	ds_write_b16 v19, v27 offset:544
	ds_write_b16_d16_hi v19, v27 offset:816
	ds_write_b16 v19, v28 offset:1088
	ds_write_b16_d16_hi v19, v28 offset:1360
	ds_write_b16 v19, v36 offset:1632
	ds_write_b16_d16_hi v19, v36 offset:1904
	v_add_u32_e32 v46, s10, v59
	v_ashrrev_i32_e32 v47, 31, v46
	v_lshlrev_b64 v[34:35], 6, v[46:47]
	v_lshl_add_u64 v[42:43], s[0:1], 0, v[34:35]
	s_waitcnt vmcnt(1)
	v_cndmask_b32_e32 v13, v16, v16, vcc
	v_cndmask_b32_e32 v19, v17, v17, vcc
	v_cndmask_b32_e32 v18, v14, v18, vcc
	v_cmp_gt_i32_e32 vcc, v11, v58
	s_waitcnt vmcnt(0)
	s_nop 0
	v_cndmask_b32_e32 v22, v22, v26, vcc
	v_cndmask_b32_e32 v25, v25, v25, vcc
	v_cndmask_b32_e32 v24, v24, v24, vcc
	v_cndmask_b32_e32 v23, v23, v23, vcc
	v_cmp_lt_i32_e32 vcc, v7, v58
	v_mad_u64_u32 v[26:27], s[12:13], v58, s33, v[2:3]
	s_nop 0
	v_cndmask_b32_e32 v14, v18, v14, vcc
	v_cndmask_b32_e32 v17, v19, v17, vcc
	v_cndmask_b32_e32 v13, v13, v16, vcc
	v_cndmask_b32_e32 v15, 0, v15, vcc
	v_cmp_le_i32_e32 vcc, v8, v58
	s_nop 1
	v_cvt_pk_bf16_f32 v14, v14, v15
	s_nop 1
	v_cndmask_b32_e32 v16, 0, v23, vcc
	v_cmp_le_i32_e32 vcc, v9, v58
	s_nop 1
	v_cndmask_b32_e32 v18, 0, v24, vcc
	v_cmp_le_i32_e32 vcc, v10, v58
	s_nop 1
	v_cndmask_b32_e32 v19, 0, v25, vcc
	v_cmp_le_i32_e32 vcc, v5, v58
	s_nop 1
	v_cndmask_b32_e32 v13, 0, v13, vcc
	v_cmp_le_i32_e32 vcc, v6, v58
	s_nop 1
	v_cndmask_b32_e32 v17, 0, v17, vcc
	s_nop 1
	v_cvt_pk_bf16_f32 v15, v13, v17
	s_nop 1
	v_cvt_pk_bf16_f32 v16, v22, v16
	s_nop 1
	v_cvt_pk_bf16_f32 v17, v18, v19
	v_mov_b32_e32 v22, v144
	v_mov_b32_e32 v23, v145
	v_mov_b32_e32 v24, v146
	v_mov_b32_e32 v25, v147
	v_mov_b32_e32 v34, v152
	v_mov_b32_e32 v35, v153
	v_mov_b32_e32 v36, v154
	v_mov_b32_e32 v37, v155
	v_mov_b32_e32 v38, v148
	v_mov_b32_e32 v39, v149
	v_mov_b32_e32 v40, v150
	v_mov_b32_e32 v41, v151
	s_nop 0
	v_mov_b32_e32 v42, v156
	v_mov_b32_e32 v43, v157
	v_mov_b32_e32 v44, v158
	v_mov_b32_e32 v45, v159
	v_lshlrev_b64 v[18:19], 11, v[46:47]
	v_lshl_add_u64 v[18:19], s[34:35], 0, v[18:19]
	v_lshl_add_u64 v[18:19], v[18:19], 0, s[48:49]
	v_lshl_add_u64 v[18:19], v[18:19], 0, v[20:21]
	v_mov_b32_e32 v46, v192
	v_mov_b32_e32 v47, v193
	v_mov_b32_e32 v48, v194
	v_mov_b32_e32 v49, v195
	v_mov_b32_e32 v50, v200
	v_mov_b32_e32 v51, v201
	v_mov_b32_e32 v52, v202
	v_mov_b32_e32 v53, v203
	v_mov_b32_e32 v54, v204
	v_mov_b32_e32 v55, v205
	v_mov_b32_e32 v56, v206
	v_mov_b32_e32 v57, v207
	ds_write_b128 v26, v[14:17] offset:34816
	v_lshlrev_b32_e32 v18, 7, v59
	v_ashrrev_i32_e32 v19, 31, v18
	v_lshl_add_u64 v[18:19], v[18:19], 2, s[8:9]
	v_lshl_add_u64 v[18:19], v[18:19], 0, v[0:1]
	s_waitcnt vmcnt(6)
	v_mov_b32_e32 v14, v22
	s_waitcnt vmcnt(5)
	v_mov_b32_e32 v15, v34
	v_mov_b32_e32 v34, v23
	v_mov_b32_e32 v16, v24
	v_mov_b32_e32 v17, v36
	v_mov_b32_e32 v36, v25
	s_waitcnt vmcnt(4)
	v_mov_b32_e32 v22, v38
	s_waitcnt vmcnt(3)
	v_mov_b32_e32 v23, v42
	v_mov_b32_e32 v42, v39
	v_mov_b32_e32 v24, v40
	v_mov_b32_e32 v25, v44
	v_mov_b32_e32 v44, v41
	v_pk_add_f32 v[14:15], v[14:15], v[34:35]
	v_pk_add_f32 v[16:17], v[16:17], v[36:37]
	v_pk_add_f32 v[22:23], v[22:23], v[42:43]
	v_pk_add_f32 v[24:25], v[24:25], v[44:45]
	v_pk_add_f32 v[14:15], v[14:15], v[16:17]
	v_pk_add_f32 v[16:17], v[22:23], v[24:25]
	s_waitcnt vmcnt(2)
	v_lshlrev_b32_e32 v26, 16, v46
	v_pk_add_f32 v[14:15], v[14:15], v[16:17]
	v_and_b32_e32 v27, 0xffff0000, v46
	v_add_f32_e32 v13, v14, v15
	v_fmamk_f32 v13, v13, 0x3a800000, v29
	v_mul_f32_e32 v14, 0x4b800000, v13
	v_cmp_gt_f32_e32 vcc, s25, v13
	v_lshlrev_b32_e32 v38, 16, v47
	v_and_b32_e32 v39, 0xffff0000, v47
	v_cndmask_b32_e32 v13, v13, v14, vcc
	v_rsq_f32_e32 v13, v13
	v_lshlrev_b32_e32 v40, 16, v48
	v_and_b32_e32 v41, 0xffff0000, v48
	v_lshlrev_b32_e32 v14, 16, v49
	v_mul_f32_e32 v16, 0x45800000, v13
	v_and_b32_e32 v15, 0xffff0000, v49
	v_cndmask_b32_e32 v16, v13, v16, vcc
	v_pk_mul_f32 v[22:23], v[16:17], v[26:27] op_sel_hi:[0,1]
	v_pk_mul_f32 v[24:25], v[16:17], v[38:39] op_sel_hi:[0,1]
	v_pk_mul_f32 v[26:27], v[16:17], v[40:41] op_sel_hi:[0,1]
	v_pk_mul_f32 v[14:15], v[16:17], v[14:15] op_sel_hi:[0,1]
	s_waitcnt vmcnt(1)
	v_pk_mul_f32 v[16:17], v[52:53], v[24:25]
	v_pk_mul_f32 v[22:23], v[50:51], v[22:23]
	s_waitcnt vmcnt(0)
	v_pk_mul_f32 v[14:15], v[56:57], v[14:15]
	v_pk_mul_f32 v[24:25], v[54:55], v[26:27]
	s_nop 1
	v_cvt_pk_bf16_f32 v13, v22, v23
	s_nop 1
	v_cvt_pk_bf16_f32 v27, v16, v17
	v_cmp_gt_i32_e32 vcc, v7, v59
	s_nop 1
	v_cvt_pk_bf16_f32 v28, v24, v25
	s_nop 1
	v_cvt_pk_bf16_f32 v36, v14, v15
	v_mov_b32_e32 v14, v224
	v_mov_b32_e32 v15, v225
	v_mov_b32_e32 v16, v226
	v_mov_b32_e32 v17, v227
	v_mov_b32_e32 v22, v228
	v_mov_b32_e32 v23, v229
	v_mov_b32_e32 v24, v230
	v_mov_b32_e32 v25, v231
	v_add_u32_e32 v19, 0x600, v3
	v_mov_b32_e32 v18, s49
	v_ashrrev_i32_e32 v58, 4, v19
	v_lshl_add_u32 v19, v59, 1, v12
	v_mov_b32_e32 v26, s49
	ds_write_b16 v19, v13
	ds_write_b16_d16_hi v19, v13 offset:272
	ds_write_b16 v19, v27 offset:544
	ds_write_b16_d16_hi v19, v27 offset:816
	ds_write_b16 v19, v28 offset:1088
	ds_write_b16_d16_hi v19, v28 offset:1360
	ds_write_b16 v19, v36 offset:1632
	ds_write_b16_d16_hi v19, v36 offset:1904
	v_add_u32_e32 v46, s10, v58
	v_ashrrev_i32_e32 v47, 31, v46
	v_lshlrev_b64 v[34:35], 6, v[46:47]
	v_lshl_add_u64 v[42:43], s[0:1], 0, v[34:35]
	s_waitcnt vmcnt(1)
	v_cndmask_b32_e32 v13, v16, v16, vcc
	v_cndmask_b32_e32 v19, v17, v17, vcc
	v_cndmask_b32_e32 v18, v14, v18, vcc
	v_cmp_gt_i32_e32 vcc, v11, v59
	s_waitcnt vmcnt(0)
	s_nop 0
	v_cndmask_b32_e32 v22, v22, v26, vcc
	v_cndmask_b32_e32 v25, v25, v25, vcc
	v_cndmask_b32_e32 v24, v24, v24, vcc
	v_cndmask_b32_e32 v23, v23, v23, vcc
	v_cmp_lt_i32_e32 vcc, v7, v59
	s_nop 1
	v_cndmask_b32_e32 v14, v18, v14, vcc
	v_cndmask_b32_e32 v17, v19, v17, vcc
	v_cndmask_b32_e32 v13, v13, v16, vcc
	v_cndmask_b32_e32 v15, 0, v15, vcc
	v_cmp_le_i32_e32 vcc, v8, v59
	s_nop 1
	v_cvt_pk_bf16_f32 v14, v14, v15
	s_nop 1
	v_cndmask_b32_e32 v16, 0, v23, vcc
	v_cmp_le_i32_e32 vcc, v9, v59
	s_nop 1
	v_cndmask_b32_e32 v18, 0, v24, vcc
	v_cmp_le_i32_e32 vcc, v10, v59
	s_nop 1
	v_cndmask_b32_e32 v19, 0, v25, vcc
	v_cmp_le_i32_e32 vcc, v5, v59
	s_nop 1
	v_cndmask_b32_e32 v13, 0, v13, vcc
	v_cmp_le_i32_e32 vcc, v6, v59
	s_nop 1
	v_cndmask_b32_e32 v17, 0, v17, vcc
	s_nop 1
	v_cvt_pk_bf16_f32 v15, v13, v17
	s_nop 1
	v_cvt_pk_bf16_f32 v16, v22, v16
	s_nop 1
	v_cvt_pk_bf16_f32 v17, v18, v19
	v_mov_b32_e32 v22, v160
	v_mov_b32_e32 v23, v161
	v_mov_b32_e32 v24, v162
	v_mov_b32_e32 v25, v163
	v_mov_b32_e32 v34, v168
	v_mov_b32_e32 v35, v169
	v_mov_b32_e32 v36, v170
	v_mov_b32_e32 v37, v171
	v_mov_b32_e32 v38, v164
	v_mov_b32_e32 v39, v165
	v_mov_b32_e32 v40, v166
	v_mov_b32_e32 v41, v167
	s_nop 0
	v_mov_b32_e32 v42, v172
	v_mov_b32_e32 v43, v173
	v_mov_b32_e32 v44, v174
	v_mov_b32_e32 v45, v175
	v_lshlrev_b64 v[18:19], 11, v[46:47]
	v_lshl_add_u64 v[18:19], s[34:35], 0, v[18:19]
	v_lshl_add_u64 v[18:19], v[18:19], 0, s[48:49]
	v_lshl_add_u64 v[18:19], v[18:19], 0, v[20:21]
	v_mov_b32_e32 v46, v196
	v_mov_b32_e32 v47, v197
	v_mov_b32_e32 v48, v198
	v_mov_b32_e32 v49, v199
	v_mov_b32_e32 v50, v200
	v_mov_b32_e32 v51, v201
	v_mov_b32_e32 v52, v202
	v_mov_b32_e32 v53, v203
	v_mov_b32_e32 v54, v204
	v_mov_b32_e32 v55, v205
	v_mov_b32_e32 v56, v206
	v_mov_b32_e32 v57, v207
	v_lshlrev_b32_e32 v18, 7, v58
	v_ashrrev_i32_e32 v19, 31, v18
	v_mad_u64_u32 v[26:27], s[2:3], v59, s33, v[2:3]
	v_lshl_add_u64 v[18:19], v[18:19], 2, s[8:9]
	v_lshl_add_u64 v[0:1], v[18:19], 0, v[0:1]
	ds_write_b128 v26, v[14:17] offset:34816
	s_waitcnt vmcnt(6)
	v_mov_b32_e32 v14, v22
	s_waitcnt vmcnt(5)
	v_mov_b32_e32 v15, v34
	v_mov_b32_e32 v34, v23
	v_mov_b32_e32 v16, v24
	v_mov_b32_e32 v17, v36
	v_mov_b32_e32 v36, v25
	s_waitcnt vmcnt(4)
	v_mov_b32_e32 v18, v38
	s_waitcnt vmcnt(3)
	v_mov_b32_e32 v19, v42
	v_mov_b32_e32 v42, v39
	v_mov_b32_e32 v22, v40
	v_mov_b32_e32 v23, v44
	v_mov_b32_e32 v44, v41
	v_pk_add_f32 v[14:15], v[14:15], v[34:35]
	v_pk_add_f32 v[16:17], v[16:17], v[36:37]
	v_pk_add_f32 v[18:19], v[18:19], v[42:43]
	v_pk_add_f32 v[22:23], v[22:23], v[44:45]
	v_pk_add_f32 v[14:15], v[14:15], v[16:17]
	v_pk_add_f32 v[16:17], v[18:19], v[22:23]
	s_waitcnt vmcnt(2)
	v_lshlrev_b32_e32 v24, 16, v46
	v_pk_add_f32 v[14:15], v[14:15], v[16:17]
	v_and_b32_e32 v25, 0xffff0000, v46
	v_add_f32_e32 v13, v14, v15
	v_fmamk_f32 v13, v13, 0x3a800000, v29
	v_mul_f32_e32 v14, 0x4b800000, v13
	v_cmp_gt_f32_e32 vcc, s25, v13
	v_lshlrev_b32_e32 v26, 16, v47
	v_and_b32_e32 v27, 0xffff0000, v47
	v_cndmask_b32_e32 v13, v13, v14, vcc
	v_rsq_f32_e32 v13, v13
	v_lshlrev_b32_e32 v38, 16, v48
	v_and_b32_e32 v39, 0xffff0000, v48
	v_lshlrev_b32_e32 v14, 16, v49
	v_mul_f32_e32 v16, 0x45800000, v13
	v_and_b32_e32 v15, 0xffff0000, v49
	v_cndmask_b32_e32 v16, v13, v16, vcc
	v_pk_mul_f32 v[18:19], v[16:17], v[24:25] op_sel_hi:[0,1]
	v_pk_mul_f32 v[22:23], v[16:17], v[26:27] op_sel_hi:[0,1]
	v_pk_mul_f32 v[24:25], v[16:17], v[38:39] op_sel_hi:[0,1]
	v_pk_mul_f32 v[14:15], v[16:17], v[14:15] op_sel_hi:[0,1]
	s_waitcnt vmcnt(1)
	v_pk_mul_f32 v[16:17], v[52:53], v[22:23]
	s_waitcnt vmcnt(0)
	v_pk_mul_f32 v[14:15], v[56:57], v[14:15]
	v_pk_mul_f32 v[22:23], v[54:55], v[24:25]
	v_pk_mul_f32 v[18:19], v[50:51], v[18:19]
	v_ashrrev_i32_e32 v41, 2, v3
	s_nop 1
	v_cvt_pk_bf16_f32 v28, v18, v19
	s_nop 1
	v_cvt_pk_bf16_f32 v38, v16, v17
	s_nop 1
	v_cvt_pk_bf16_f32 v39, v22, v23
	s_nop 1
	v_cvt_pk_bf16_f32 v15, v14, v15
	v_mov_b32_e32 v22, v232
	v_mov_b32_e32 v23, v233
	v_mov_b32_e32 v24, v234
	v_mov_b32_e32 v25, v235
	v_mov_b32_e32 v34, v236
	v_mov_b32_e32 v35, v237
	v_mov_b32_e32 v36, v238
	v_mov_b32_e32 v37, v239
	v_mov_b32_e32 v0, s49
	v_bfe_u32 v40, v3, 4, 2
	v_and_b32_e32 v1, -16, v41
	v_or_b32_e32 v13, s11, v4
	v_cmp_gt_i32_e32 vcc, v7, v58
	v_mov_b32_e32 v14, s49
	v_lshl_add_u32 v42, v58, 1, v12
	v_ashrrev_i32_e32 v17, 31, v1
	v_lshl_or_b32 v16, v40, 2, v1
	v_lshlrev_b32_e32 v46, 2, v13
	v_mad_u64_u32 v[12:13], s[2:3], v58, s33, v[2:3]
	ds_write_b16 v42, v28
	ds_write_b16_d16_hi v42, v28 offset:272
	ds_write_b16 v42, v38 offset:544
	ds_write_b16_d16_hi v42, v38 offset:816
	ds_write_b16 v42, v39 offset:1088
	ds_write_b16_d16_hi v42, v39 offset:1360
	ds_write_b16 v42, v15 offset:1632
	ds_write_b16_d16_hi v42, v15 offset:1904
	v_or_b32_e32 v18, s10, v4
	v_lshl_or_b32 v20, v18, 10, s11
	v_lshl_add_u64 v[18:19], v[16:17], 0, v[20:21]
	v_lshlrev_b64 v[18:19], 1, v[18:19]
	v_lshl_add_u64 v[26:27], s[30:31], 0, v[18:19]
	v_lshl_add_u64 v[18:19], s[36:37], 0, v[18:19]
	v_mov_b32_e32 v43, v21
	v_or_b32_e32 v42, 0x14000, v20
	s_waitcnt vmcnt(1)
	v_cndmask_b32_e32 v1, v24, v24, vcc
	v_cndmask_b32_e32 v2, v25, v25, vcc
	v_cndmask_b32_e32 v0, v22, v0, vcc
	v_cmp_gt_i32_e32 vcc, v11, v58
	s_waitcnt vmcnt(0)
	s_nop 0
	v_cndmask_b32_e32 v11, v34, v14, vcc
	v_cndmask_b32_e32 v13, v37, v37, vcc
	v_cndmask_b32_e32 v14, v36, v36, vcc
	v_cndmask_b32_e32 v15, v35, v35, vcc
	v_cmp_lt_i32_e32 vcc, v7, v58
	s_nop 1
	v_cndmask_b32_e32 v0, v0, v22, vcc
	v_cndmask_b32_e32 v2, v2, v25, vcc
	v_cndmask_b32_e32 v1, v1, v24, vcc
	v_cndmask_b32_e32 v7, 0, v23, vcc
	v_cmp_le_i32_e32 vcc, v8, v58
	s_nop 1
	v_cndmask_b32_e32 v8, 0, v15, vcc
	v_cmp_le_i32_e32 vcc, v9, v58
	s_nop 1
	v_cndmask_b32_e32 v9, 0, v14, vcc
	v_cmp_le_i32_e32 vcc, v10, v58
	s_nop 1
	v_cndmask_b32_e32 v10, 0, v13, vcc
	v_cmp_le_i32_e32 vcc, v5, v58
	s_nop 1
	v_cndmask_b32_e32 v1, 0, v1, vcc
	v_cmp_le_i32_e32 vcc, v6, v58
	s_nop 1
	v_cvt_pk_bf16_f32 v6, v0, v7
	v_lshl_add_u32 v0, v40, 4, 16
	v_mad_u32_u24 v47, v4, s33, v0
	v_cndmask_b32_e32 v2, 0, v2, vcc
	s_nop 1
	v_cvt_pk_bf16_f32 v7, v1, v2
	s_nop 1
	v_cvt_pk_bf16_f32 v8, v11, v8
	s_nop 1
	v_cvt_pk_bf16_f32 v9, v9, v10
	ds_write_b128 v12, v[6:9] offset:34816
	s_waitcnt lgkmcnt(0)
	s_barrier
	global_load_dwordx2 v[26:27], v[26:27], off
	s_nop 0
	global_load_dword v28, v46, s[46:47]
	v_mov_b32_e32 v1, v21
	v_bfi_b32 v2, -16, v41, v3
	v_mad_u64_u32 v[2:3], s[2:3], v2, s33, v[0:1]
	ds_read_b128 v[4:7], v2
	ds_read_b128 v[22:25], v47 offset:34816
	s_waitcnt lgkmcnt(0)
	v_mfma_f32_16x16x32_bf16 v[22:25], v[4:7], v[22:25], 0
	v_or_b32_e32 v0, 0x4000, v20
	v_lshl_add_u64 v[0:1], v[16:17], 0, v[0:1]
	v_lshlrev_b64 v[34:35], 1, v[0:1]
	v_lshl_add_u64 v[36:37], s[30:31], 0, v[34:35]
	ds_read_b128 v[12:15], v2 offset:64
	ds_read_b128 v[8:11], v2 offset:128
	ds_read_b128 v[0:3], v2 offset:192
	v_lshl_add_u64 v[34:35], s[36:37], 0, v[34:35]
	s_mov_b64 s[2:3], 0
	s_waitcnt vmcnt(1)
	v_lshlrev_b32_e32 v38, 16, v26
	s_waitcnt vmcnt(0)
	v_add_f32_e32 v22, v22, v28
	v_and_b32_e32 v26, 0xffff0000, v26
	v_add_f32_e32 v23, v23, v28
	v_lshlrev_b32_e32 v39, 16, v27
	v_add_f32_e32 v24, v24, v28
	v_and_b32_e32 v27, 0xffff0000, v27
	v_add_f32_e32 v25, v25, v28
	v_mul_f32_e32 v22, v22, v38
	v_mul_f32_e32 v23, v23, v26
	v_mul_f32_e32 v24, v24, v39
	v_mul_f32_e32 v25, v25, v27
	s_nop 1
	v_cvt_pk_bf16_f32 v22, v22, v23
	s_nop 1
	v_cvt_pk_bf16_f32 v23, v24, v25
	global_store_dwordx2 v[18:19], v[22:23], off
	global_load_dwordx2 v[18:19], v[36:37], off
	s_nop 0
	global_load_dword v28, v46, s[46:47] offset:64
	ds_read_b128 v[22:25], v47 offset:39168
	s_waitcnt lgkmcnt(0)
	v_mfma_f32_16x16x32_bf16 v[22:25], v[4:7], v[22:25], 0
	v_mov_b32_e32 v27, v21
	v_or_b32_e32 v26, 0x8000, v20
	v_lshl_add_u64 v[26:27], v[16:17], 0, v[26:27]
	v_lshlrev_b64 v[26:27], 1, v[26:27]
	v_lshl_add_u64 v[36:37], s[30:31], 0, v[26:27]
	v_lshl_add_u64 v[26:27], s[36:37], 0, v[26:27]
	s_waitcnt vmcnt(1)
	v_lshlrev_b32_e32 v38, 16, v18
	v_and_b32_e32 v18, 0xffff0000, v18
	s_waitcnt vmcnt(0)
	v_add_f32_e32 v23, v23, v28
	v_lshlrev_b32_e32 v39, 16, v19
	v_and_b32_e32 v19, 0xffff0000, v19
	v_add_f32_e32 v25, v25, v28
	v_add_f32_e32 v22, v22, v28
	v_add_f32_e32 v24, v24, v28
	v_mul_f32_e32 v18, v23, v18
	v_mul_f32_e32 v19, v25, v19
	v_mul_f32_e32 v22, v22, v38
	v_mul_f32_e32 v23, v24, v39
	s_nop 1
	v_cvt_pk_bf16_f32 v18, v22, v18
	s_nop 1
	v_cvt_pk_bf16_f32 v19, v23, v19
	global_store_dwordx2 v[34:35], v[18:19], off
	global_load_dwordx2 v[18:19], v[36:37], off
	s_nop 0
	global_load_dword v28, v46, s[46:47] offset:128
	ds_read_b128 v[22:25], v47 offset:43520
	v_mov_b32_e32 v35, v21
	v_or_b32_e32 v34, 0xc000, v20
	v_lshl_add_u64 v[38:39], v[16:17], 0, v[34:35]
	ds_read_b128 v[34:37], v47 offset:43584
	s_waitcnt lgkmcnt(1)
	v_mfma_f32_16x16x32_bf16 v[22:25], v[4:7], v[22:25], 0
	v_lshlrev_b64 v[38:39], 1, v[38:39]
	v_lshl_add_u64 v[40:41], s[30:31], 0, v[38:39]
	v_lshl_add_u64 v[38:39], s[36:37], 0, v[38:39]
	s_waitcnt lgkmcnt(0)
	v_mfma_f32_16x16x32_bf16 v[22:25], v[12:15], v[34:37], v[22:25]
	s_waitcnt vmcnt(1)
	v_lshlrev_b32_e32 v34, 16, v18
	v_and_b32_e32 v18, 0xffff0000, v18
	s_waitcnt vmcnt(0)
	s_nop 3
	v_add_f32_e32 v23, v23, v28
	v_lshlrev_b32_e32 v35, 16, v19
	v_and_b32_e32 v19, 0xffff0000, v19
	v_add_f32_e32 v25, v25, v28
	v_add_f32_e32 v22, v22, v28
	v_add_f32_e32 v24, v24, v28
	v_mul_f32_e32 v18, v23, v18
	v_mul_f32_e32 v19, v25, v19
	v_mul_f32_e32 v22, v22, v34
	v_mul_f32_e32 v23, v24, v35
	s_nop 1
	v_cvt_pk_bf16_f32 v18, v22, v18
	s_nop 1
	v_cvt_pk_bf16_f32 v19, v23, v19
	global_store_dwordx2 v[26:27], v[18:19], off
	global_load_dwordx2 v[18:19], v[40:41], off
	s_nop 0
	global_load_dword v28, v46, s[46:47] offset:192
	ds_read_b128 v[22:25], v47 offset:47872
	ds_read_b128 v[34:37], v47 offset:47936
	s_waitcnt lgkmcnt(1)
	v_mfma_f32_16x16x32_bf16 v[22:25], v[4:7], v[22:25], 0
	v_mov_b32_e32 v27, v21
	v_or_b32_e32 v26, 0x10000, v20
	v_lshl_add_u64 v[26:27], v[16:17], 0, v[26:27]
	s_waitcnt lgkmcnt(0)
	v_mfma_f32_16x16x32_bf16 v[22:25], v[12:15], v[34:37], v[22:25]
	v_lshlrev_b64 v[26:27], 1, v[26:27]
	v_lshl_add_u64 v[40:41], s[30:31], 0, v[26:27]
	v_lshl_add_u64 v[26:27], s[36:37], 0, v[26:27]
	s_waitcnt vmcnt(1)
	v_lshlrev_b32_e32 v34, 16, v18
	v_and_b32_e32 v18, 0xffff0000, v18
	s_waitcnt vmcnt(0)
	s_nop 0
	v_add_f32_e32 v23, v23, v28
	v_lshlrev_b32_e32 v35, 16, v19
	v_and_b32_e32 v19, 0xffff0000, v19
	v_add_f32_e32 v25, v25, v28
	v_add_f32_e32 v22, v22, v28
	v_add_f32_e32 v24, v24, v28
	v_mul_f32_e32 v18, v23, v18
	v_mul_f32_e32 v19, v25, v19
	v_mul_f32_e32 v22, v22, v34
	v_mul_f32_e32 v23, v24, v35
	s_nop 1
	v_cvt_pk_bf16_f32 v18, v22, v18
	s_nop 1
	v_cvt_pk_bf16_f32 v19, v23, v19
	global_store_dwordx2 v[38:39], v[18:19], off
	global_load_dwordx2 v[18:19], v[40:41], off
	s_nop 0
	global_load_dword v28, v46, s[46:47] offset:256
	ds_read_b128 v[22:25], v47 offset:52224
	ds_read_b128 v[34:37], v47 offset:52288
	s_waitcnt lgkmcnt(1)
	v_mfma_f32_16x16x32_bf16 v[22:25], v[4:7], v[22:25], 0
	ds_read_b128 v[38:41], v47 offset:52352
	s_waitcnt lgkmcnt(1)
	v_mfma_f32_16x16x32_bf16 v[22:25], v[12:15], v[34:37], v[22:25]
	v_lshl_add_u64 v[34:35], v[16:17], 0, v[42:43]
	v_lshlrev_b64 v[42:43], 1, v[34:35]
	s_waitcnt vmcnt(1)
	v_lshlrev_b32_e32 v34, 16, v18
	s_waitcnt lgkmcnt(0)
	v_mfma_f32_16x16x32_bf16 v[22:25], v[8:11], v[38:41], v[22:25]
	v_and_b32_e32 v18, 0xffff0000, v18
	v_lshlrev_b32_e32 v35, 16, v19
	v_and_b32_e32 v19, 0xffff0000, v19
	v_lshl_add_u64 v[38:39], s[30:31], 0, v[42:43]
	v_lshl_add_u64 v[42:43], s[36:37], 0, v[42:43]
	s_waitcnt vmcnt(0)
	s_nop 1
	v_add_f32_e32 v23, v23, v28
	v_add_f32_e32 v25, v25, v28
	v_add_f32_e32 v22, v22, v28
	v_add_f32_e32 v24, v24, v28
	v_mul_f32_e32 v18, v23, v18
	v_mul_f32_e32 v19, v25, v19
	v_mul_f32_e32 v22, v22, v34
	v_mul_f32_e32 v23, v24, v35
	s_nop 1
	v_cvt_pk_bf16_f32 v18, v22, v18
	s_nop 1
	v_cvt_pk_bf16_f32 v19, v23, v19
	global_store_dwordx2 v[26:27], v[18:19], off
	global_load_dword v26, v46, s[46:47] offset:320
	ds_read_b128 v[22:25], v47 offset:56576
	ds_read_b128 v[34:37], v47 offset:56640
	global_load_dwordx2 v[18:19], v[38:39], off
	s_waitcnt lgkmcnt(1)
	v_mfma_f32_16x16x32_bf16 v[22:25], v[4:7], v[22:25], 0
	v_mov_b32_e32 v27, v21
	s_waitcnt vmcnt(0)
	v_lshlrev_b32_e32 v28, 16, v18
	s_waitcnt lgkmcnt(0)
	v_mfma_f32_16x16x32_bf16 v[22:25], v[12:15], v[34:37], v[22:25]
	ds_read_b128 v[34:37], v47 offset:56704
	v_and_b32_e32 v18, 0xffff0000, v18
	s_waitcnt lgkmcnt(0)
	v_mfma_f32_16x16x32_bf16 v[22:25], v[8:11], v[34:37], v[22:25]
	v_lshlrev_b32_e32 v34, 16, v19
	v_and_b32_e32 v19, 0xffff0000, v19
	s_nop 5
	v_add_f32_e32 v22, v22, v26
	v_add_f32_e32 v23, v23, v26
	v_add_f32_e32 v24, v24, v26
	v_add_f32_e32 v25, v25, v26
	v_or_b32_e32 v26, 0x18000, v20
	v_lshl_add_u64 v[26:27], v[16:17], 0, v[26:27]
	v_mul_f32_e32 v18, v23, v18
	v_mul_f32_e32 v19, v25, v19
	v_lshlrev_b64 v[26:27], 1, v[26:27]
	v_mul_f32_e32 v22, v22, v28
	v_mul_f32_e32 v23, v24, v34
	s_nop 1
	v_cvt_pk_bf16_f32 v18, v22, v18
	s_nop 1
	v_cvt_pk_bf16_f32 v19, v23, v19
	v_lshl_add_u64 v[44:45], s[30:31], 0, v[26:27]
	global_store_dwordx2 v[42:43], v[18:19], off
	global_load_dwordx2 v[18:19], v[44:45], off
	ds_read_b128 v[22:25], v47 offset:60928
	ds_read_b128 v[34:37], v47 offset:60992
	global_load_dword v28, v46, s[46:47] offset:384
	s_waitcnt lgkmcnt(1)
	v_mfma_f32_16x16x32_bf16 v[22:25], v[4:7], v[22:25], 0
	ds_read_b128 v[38:41], v47 offset:61056
	v_or_b32_e32 v20, 0x1c000, v20
	v_lshl_add_u64 v[16:17], v[16:17], 0, v[20:21]
	s_waitcnt lgkmcnt(1)
	v_mfma_f32_16x16x32_bf16 v[22:25], v[12:15], v[34:37], v[22:25]
	ds_read_b128 v[34:37], v47 offset:61120
	v_lshl_add_u64 v[26:27], s[36:37], 0, v[26:27]
	s_waitcnt lgkmcnt(1)
	v_mfma_f32_16x16x32_bf16 v[22:25], v[8:11], v[38:41], v[22:25]
	s_waitcnt lgkmcnt(0)
	v_mfma_f32_16x16x32_bf16 v[22:25], v[0:3], v[34:37], v[22:25]
	v_lshlrev_b64 v[36:37], 1, v[16:17]
	v_lshl_add_u64 v[38:39], s[30:31], 0, v[36:37]
	s_waitcnt vmcnt(1)
	v_lshlrev_b32_e32 v34, 16, v18
	v_and_b32_e32 v18, 0xffff0000, v18
	v_lshlrev_b32_e32 v35, 16, v19
	s_waitcnt vmcnt(0)
	s_nop 0
	v_add_f32_e32 v22, v22, v28
	v_add_f32_e32 v23, v23, v28
	v_add_f32_e32 v24, v24, v28
	v_and_b32_e32 v19, 0xffff0000, v19
	v_add_f32_e32 v25, v25, v28
	v_mul_f32_e32 v22, v22, v34
	v_mul_f32_e32 v18, v23, v18
	v_mul_f32_e32 v23, v24, v35
	v_mul_f32_e32 v19, v25, v19
	s_nop 1
	v_cvt_pk_bf16_f32 v34, v22, v18
	s_nop 1
	v_cvt_pk_bf16_f32 v35, v23, v19
	ds_read_b128 v[22:25], v47 offset:65280
	ds_read_b128 v[16:19], v47 offset:65344
	s_waitcnt lgkmcnt(1)
	v_mfma_f32_16x16x32_bf16 v[4:7], v[4:7], v[22:25], 0
	ds_read_b128 v[22:25], v47 offset:65408
	global_store_dwordx2 v[26:27], v[34:35], off
	s_waitcnt lgkmcnt(1)
	v_mfma_f32_16x16x32_bf16 v[4:7], v[12:15], v[16:19], v[4:7]
	ds_read_b128 v[12:15], v47 offset:65472
	global_load_dwordx2 v[16:17], v[38:39], off
	s_waitcnt lgkmcnt(1)
	v_mfma_f32_16x16x32_bf16 v[4:7], v[8:11], v[22:25], v[4:7]
	global_load_dword v10, v46, s[46:47] offset:448
	v_lshl_add_u64 v[8:9], s[36:37], 0, v[36:37]
	s_waitcnt lgkmcnt(0)
	v_mfma_f32_16x16x32_bf16 v[0:3], v[0:3], v[12:15], v[4:7]
	s_waitcnt vmcnt(1)
	s_nop 2
	v_lshlrev_b32_e32 v4, 16, v16
	v_and_b32_e32 v5, 0xffff0000, v16
	v_lshlrev_b32_e32 v6, 16, v17
	s_waitcnt vmcnt(0)
	v_add_f32_e32 v0, v0, v10
	v_add_f32_e32 v1, v1, v10
	v_add_f32_e32 v2, v2, v10
	v_and_b32_e32 v7, 0xffff0000, v17
	v_add_f32_e32 v3, v3, v10
	v_mul_f32_e32 v0, v0, v4
	v_mul_f32_e32 v1, v1, v5
	v_mul_f32_e32 v2, v2, v6
	v_mul_f32_e32 v3, v3, v7
	s_nop 1
	v_cvt_pk_bf16_f32 v0, v0, v1
	s_nop 1
	v_cvt_pk_bf16_f32 v1, v2, v3
	global_store_dwordx2 v[8:9], v[0:1], off
	s_barrier
.LBB0_1358:
	s_andn2_b64 vcc, exec, s[2:3]
	s_cbranch_vccnz .LBB0_1355
	s_bfe_u32 s59, s58, 0x40002
	v_mov_b32_e32 v69, v183
	s_lshl_b32 s10, s58, 5
	s_and_b32 s2, s10, 0xfffff800
	s_lshl_b32 s3, s59, 7
	v_bfe_u32 v71, v69, 6, 1
	v_and_b32_e32 v70, 15, v69
	s_or_b32 s12, s3, s2
	v_lshlrev_b32_e32 v73, 6, v71
	s_and_b32 s8, s58, 3
	v_ashrrev_i32_e32 v72, 7, v69
	v_or3_b32 v0, v73, s12, v70
	v_lshl_add_u32 v24, s8, 2, v72
	v_ashrrev_i32_e32 v1, 31, v0
	v_lshlrev_b64 v[0:1], 11, v[0:1]
	v_lshlrev_b32_e32 v22, 6, v24
	v_bfe_u32 v34, v69, 4, 2
	v_lshl_add_u64 v[0:1], s[4:5], 0, v[0:1]
	v_ashrrev_i32_e32 v23, 31, v22
	v_lshl_add_u64 v[0:1], v[22:23], 1, v[0:1]
	v_lshlrev_b32_e32 v20, 4, v34
	v_lshl_add_u64 v[0:1], v[0:1], 0, v[20:21]
	global_load_dwordx4 v[8:11], v[0:1], off
	global_load_dwordx4 v[12:15], v[0:1], off offset:64
	v_and_b32_e32 v6, 7, v69
	s_cmp_lg_u32 s59, 0
	v_ashrrev_i32_e32 v1, 3, v69
	s_cselect_b64 s[2:3], -1, 0
	v_lshlrev_b32_e32 v2, 3, v6
	v_cmp_lt_i32_e32 vcc, s52, v1
	v_mov_b32_e32 v16, 0
	s_addk_i32 s12, 0xff80
	s_lshl_b32 s11, s8, 6
	s_or_b64 s[14:15], s[2:3], vcc
	v_mov_b32_e32 v0, 0
	v_lshlrev_b32_e32 v26, 1, v2
	v_mov_b32_e32 v2, 0
	v_mov_b32_e32 v3, 0
	v_mov_b32_e32 v4, 0
	v_mov_b32_e32 v5, 0
	v_mov_b32_e32 v17, v16
	v_mov_b32_e32 v18, v16
	v_mov_b32_e32 v19, v16
	s_lshl_b32 s48, s11, 1
	v_mov_b32_e32 v128, v1
	v_add_u32_e32 v2, s12, v1
	v_ashrrev_i32_e32 v3, 31, v2
	v_lshlrev_b64 v[2:3], 9, v[2:3]
	v_lshl_add_u64 v[4:5], s[6:7], 0, v[2:3]
	v_lshl_add_u64 v[2:3], s[26:27], 0, v[2:3]
	v_lshl_add_u64 v[4:5], v[4:5], 0, s[48:49]
	v_lshl_add_u64 v[2:3], v[2:3], 0, s[48:49]
	v_mov_b32_e32 v27, v21
	v_lshl_add_u64 v[4:5], v[4:5], 0, v[26:27]
	v_lshl_add_u64 v[2:3], v[2:3], 0, v[26:27]
	s_mov_b32 s14, 0x8000
	s_mov_b32 s15, 0
	v_lshl_add_u64 v[130:131], v[4:5], 0, s[14:15]
	v_lshl_add_u64 v[132:133], v[2:3], 0, s[14:15]
	v_lshl_add_u64 v[134:135], v[130:131], 0, s[14:15]
	v_lshl_add_u64 v[136:137], v[132:133], 0, s[14:15]
	v_lshl_add_u64 v[138:139], v[134:135], 0, s[14:15]
	v_lshl_add_u64 v[140:141], v[136:137], 0, s[14:15]
	global_load_dwordx4 v[150:153], v[134:135], off
	global_load_dwordx4 v[154:157], v[136:137], off
	global_load_dwordx4 v[158:161], v[138:139], off
	global_load_dwordx4 v[162:165], v[140:141], off
	v_mov_b32_e32 v16, 0
	v_mov_b32_e32 v17, 0
	v_mov_b32_e32 v18, 0
	v_mov_b32_e32 v19, 0
	v_mov_b32_e32 v142, 0
	v_mov_b32_e32 v143, 0
	v_mov_b32_e32 v144, 0
	v_mov_b32_e32 v145, 0
	v_mov_b32_e32 v146, 0
	v_mov_b32_e32 v147, 0
	v_mov_b32_e32 v148, 0
	v_mov_b32_e32 v149, 0
	v_mov_b32_e32 v166, 0
	v_mov_b32_e32 v167, 0
	v_mov_b32_e32 v168, 0
	v_mov_b32_e32 v169, 0
	s_and_saveexec_b64 s[8:9], s[2:3]
	s_cbranch_execz .Lattn_stg_skip_L1
	global_load_dwordx4 v[16:19], v[4:5], off
	global_load_dwordx4 v[142:145], v[2:3], off
	global_load_dwordx4 v[146:149], v[130:131], off
	global_load_dwordx4 v[166:169], v[132:133], off
.Lattn_stg_skip_L1:
	s_or_b64 exec, exec, s[8:9]
	v_lshl_add_u32 v28, v6, 4, 16
	s_movk_i32 s8, 0x1070
	v_mad_u32_u24 v25, v6, s8, v28
	v_mad_u32_u24 v0, v128, s53, v28
	v_lshl_add_u32 v1, v128, 1, v25
	s_waitcnt vmcnt(0)
	ds_write_b128 v0, v[16:19]
	ds_write_b128 v0, v[146:149] offset:9216
	ds_write_b128 v0, v[150:153] offset:18432
	ds_write_b128 v0, v[158:161] offset:27648
	ds_write_b16 v1, v142 offset:36864
	ds_write_b16_d16_hi v1, v142 offset:37392
	ds_write_b16 v1, v143 offset:37920
	ds_write_b16_d16_hi v1, v143 offset:38448
	ds_write_b16 v1, v144 offset:38976
	ds_write_b16_d16_hi v1, v144 offset:39504
	ds_write_b16 v1, v145 offset:40032
	ds_write_b16_d16_hi v1, v145 offset:40560
	ds_write_b16 v1, v166 offset:36992
	ds_write_b16_d16_hi v1, v166 offset:37520
	ds_write_b16 v1, v167 offset:38048
	ds_write_b16_d16_hi v1, v167 offset:38576
	ds_write_b16 v1, v168 offset:39104
	ds_write_b16_d16_hi v1, v168 offset:39632
	ds_write_b16 v1, v169 offset:40160
	ds_write_b16_d16_hi v1, v169 offset:40688
	ds_write_b16 v1, v154 offset:37120
	ds_write_b16_d16_hi v1, v154 offset:37648
	ds_write_b16 v1, v155 offset:38176
	ds_write_b16_d16_hi v1, v155 offset:38704
	ds_write_b16 v1, v156 offset:39232
	ds_write_b16_d16_hi v1, v156 offset:39760
	ds_write_b16 v1, v157 offset:40288
	ds_write_b16_d16_hi v1, v157 offset:40816
	ds_write_b16 v1, v162 offset:37248
	ds_write_b16_d16_hi v1, v162 offset:37776
	ds_write_b16 v1, v163 offset:38304
	ds_write_b16_d16_hi v1, v163 offset:38832
	ds_write_b16 v1, v164 offset:39360
	ds_write_b16_d16_hi v1, v164 offset:39888
	ds_write_b16 v1, v165 offset:40416
	ds_write_b16_d16_hi v1, v165 offset:40944
	v_add_u32_e32 v1, 1, v24
	v_cvt_f32_i32_e32 v1, v1
	v_mul_f32_e32 v0, -0.5, v1
	s_mov_b32 s2, 0xc2fc0000
	v_cmp_gt_f32_e32 vcc, s2, v0
	v_readlane_b32 s72, v254, 30
	v_ashrrev_i32_e32 v25, 31, v24
	v_cndmask_b32_e32 v0, 0, v30, vcc
	v_fmac_f32_e32 v0, -0.5, v1
	v_exp_f32_e32 v0, v0
	v_cndmask_b32_e32 v1, 0, v31, vcc
	v_readlane_b32 s76, v254, 34
	v_readlane_b32 s77, v254, 35
	v_ldexp_f32 v2, v0, v1
	s_waitcnt lgkmcnt(0)
	v_lshl_add_u64 v[0:1], v[24:25], 2, s[76:77]
	s_barrier
	global_load_dword v24, v[0:1], off offset:64
	v_lshlrev_b32_e32 v0, 2, v34
	v_sub_u32_e32 v0, v70, v0
	v_add_u32_e32 v3, -1, v0
	v_cvt_f32_i32_e32 v3, v3
	v_cvt_f32_i32_e32 v1, v0
	v_add_u32_e32 v4, -2, v0
	v_add_u32_e32 v5, -3, v0
	v_mul_f32_e64 v26, -v2, v3
	v_and_b32_e32 v3, 64, v32
	v_mul_f32_e64 v25, v1, -v2
	v_xor_b32_e32 v1, 16, v32
	v_add_u32_e32 v3, 64, v3
	v_cmp_lt_i32_e32 vcc, v1, v3
	s_and_b32 s8, s21, 0xfffff800
	s_and_b32 s9, s10, 0x780
	v_cndmask_b32_e32 v1, v32, v1, vcc
	v_lshlrev_b32_e32 v35, 2, v1
	v_xor_b32_e32 v1, 32, v32
	s_and_b32 s48, s57, 3
	v_cvt_f32_i32_e32 v4, v4
	v_cvt_f32_i32_e32 v5, v5
	v_cmp_lt_i32_e32 vcc, v1, v3
	s_cmp_eq_u32 s59, 0
	v_lshlrev_b32_e32 v74, 3, v34
	v_cndmask_b32_e32 v1, v32, v1, vcc
	s_cselect_b64 s[2:3], -1, 0
	v_lshlrev_b32_e32 v36, 2, v1
	v_cmp_gt_i32_e64 s[10:11], 0, v0
	v_cmp_gt_i32_e64 s[12:13], 1, v0
	v_cmp_gt_i32_e64 s[14:15], 2, v0
	v_cmp_gt_i32_e64 s[16:17], 3, v0
	v_lshl_add_u64 v[0:1], v[22:23], 1, s[28:29]
	v_mov_b32_e32 v75, v21
	s_or_b32 s8, s8, s9
	v_lshl_add_u64 v[16:17], v[0:1], 0, v[74:75]
	v_or_b32_e32 v0, s8, v73
	v_mul_f32_e64 v27, -v2, v4
	v_mul_f32_e64 v28, -v2, v5
	v_add_u32_e32 v18, v0, v70
	v_fmamk_f32 v37, v2, 0xc3000000, v25
	v_fmamk_f32 v38, v2, 0xc3000000, v26
	v_fmamk_f32 v39, v2, 0xc3000000, v27
	v_fmamk_f32 v40, v2, 0xc3000000, v28
	v_fmamk_f32 v41, v2, 0xc2e00000, v25
	v_fmamk_f32 v42, v2, 0xc2e00000, v26
	v_fmamk_f32 v43, v2, 0xc2e00000, v27
	v_fmamk_f32 v44, v2, 0xc2e00000, v28
	v_fmamk_f32 v45, v2, 0xc2c00000, v25
	v_fmamk_f32 v46, v2, 0xc2c00000, v26
	v_fmamk_f32 v47, v2, 0xc2c00000, v27
	v_fmamk_f32 v48, v2, 0xc2c00000, v28
	v_fmamk_f32 v49, v2, 0xc2a00000, v25
	v_fmamk_f32 v50, v2, 0xc2a00000, v26
	v_fmamk_f32 v51, v2, 0xc2a00000, v27
	v_fmamk_f32 v52, v2, 0xc2a00000, v28
	v_fmamk_f32 v53, v2, 0xc2800000, v25
	v_fmamk_f32 v54, v2, 0xc2800000, v26
	v_fmamk_f32 v55, v2, 0xc2800000, v27
	v_fmamk_f32 v56, v2, 0xc2800000, v28
	v_fmamk_f32 v57, v2, 0xc2400000, v25
	v_fmamk_f32 v58, v2, 0xc2400000, v26
	v_fmamk_f32 v59, v2, 0xc2400000, v27
	v_fmamk_f32 v60, v2, 0xc2400000, v28
	v_fmamk_f32 v61, v2, 0xc2000000, v25
	v_fmamk_f32 v62, v2, 0xc2000000, v26
	v_fmamk_f32 v63, v2, 0xc2000000, v27
	v_fmamk_f32 v64, v2, 0xc2000000, v28
	v_fmamk_f32 v65, v2, 0xc1800000, v25
	v_fmamk_f32 v66, v2, 0xc1800000, v26
	v_fmamk_f32 v67, v2, 0xc1800000, v27
	v_fmamk_f32 v68, v2, 0xc1800000, v28
	v_fmac_f32_e32 v25, 0x80000000, v2
	v_fmac_f32_e32 v26, 0x80000000, v2
	v_fmac_f32_e32 v27, 0x80000000, v2
	v_fmac_f32_e32 v28, 0x80000000, v2
	v_ashrrev_i32_e32 v19, 31, v18
	v_lshlrev_b32_e32 v2, 6, v72
	v_lshlrev_b64 v[0:1], 11, v[18:19]
	v_lshl_add_u32 v2, s48, 8, v2
	v_and_or_b32 v0, v69, 48, v0
	v_ashrrev_i32_e32 v3, 31, v2
	v_lshl_add_u64 v[0:1], v[2:3], 1, v[0:1]
	v_lshl_add_u64 v[22:23], s[0:1], 0, v[0:1]
	v_lshlrev_b32_e32 v0, 7, v71
	v_mad_u32_u24 v0, v70, s54, v0
	v_add3_u32 v69, v0, v74, s55
	v_mul_u32_u24_e32 v0, 0x90, v70
	v_mad_u32_u24 v0, v71, s56, v0
	v_add3_u32 v19, v0, v20, 16
	v_mov_b64_e32 v[0:1], v[12:13]
	v_mov_b64_e32 v[4:5], v[8:9]
	v_lshlrev_b32_e32 v34, 2, v71
	s_mov_b64 s[50:51], 0
	v_mov_b64_e32 v[2:3], v[14:15]
	v_mov_b64_e32 v[6:7], v[10:11]
	v_readlane_b32 s73, v254, 31
	v_readlane_b32 s74, v254, 32
	v_readlane_b32 s75, v254, 33
	v_readlane_b32 s78, v254, 36
	v_readlane_b32 s79, v254, 37
	v_readlane_b32 s80, v254, 38
	v_readlane_b32 s81, v254, 39
	v_readlane_b32 s82, v254, 40
	v_readlane_b32 s83, v254, 41
	v_readlane_b32 s84, v254, 42
	v_readlane_b32 s85, v254, 43
	v_readlane_b32 s86, v254, 44
	v_readlane_b32 s87, v254, 45
	s_branch .LBB0_1369
